# o5 + GEMM K-loops: load segments run at s_setprio 2 (MFMA bursts stay at 1): 28 sites
# baseline (speedup 1.0000x reference)
.LBB0_203:
	ds_read_b128 v[152:155], v148
	ds_read_b128 v[156:159], v148 offset:1024
	ds_read_b128 v[160:163], v148 offset:2048
	ds_read_b128 v[164:167], v148 offset:3072
	ds_read_b128 v[168:171], v149
	ds_read_b128 v[172:175], v149 offset:1024
	ds_read_b128 v[176:179], v149 offset:2048
	ds_read_b128 v[180:183], v149 offset:3072
	s_add_u32 s26, s24, 0xfff80080
	s_addc_u32 s27, s25, -1
	s_cmp_eq_u32 s50, 28
	s_cselect_b32 s29, s11, s27
	s_cselect_b32 s28, s46, s26
	s_cselect_b32 s27, s9, s49
	s_cselect_b32 s26, s47, s48
	v_lshl_add_u64 v[200:201], s[24:25], 0, v[138:139]
	s_add_i32 m0, s17, 0xc000
	ds_read_b128 v[184:187], v150
	ds_read_b128 v[188:191], v150 offset:1024
	ds_read_b128 v[192:195], v150 offset:2048
	ds_read_b128 v[196:199], v150 offset:3072
	ds_read_b128 v[204:207], v150 offset:4096
	ds_read_b128 v[208:211], v150 offset:5120
	ds_read_b128 v[212:215], v150 offset:6144
	ds_read_b128 v[216:219], v150 offset:7168
	global_load_lds_dwordx4 v[200:201], off
	v_lshl_add_u64 v[200:201], s[24:25], 0, v[140:141]
	s_add_i32 m0, s17, 0xe000
	s_nop 0
	global_load_lds_dwordx4 v[200:201], off
	s_waitcnt vmcnt(8)
	s_waitcnt lgkmcnt(0)
	s_barrier
	s_setprio 1
	s_waitcnt lgkmcnt(0)
	v_mfma_f32_16x16x32_bf16 v[126:129], v[152:155], v[184:187], v[126:129]
	v_mfma_f32_16x16x32_bf16 v[122:125], v[160:163], v[184:187], v[122:125]
	v_mfma_f32_16x16x32_bf16 v[110:113], v[152:155], v[192:195], v[110:113]
	v_mfma_f32_16x16x32_bf16 v[106:109], v[160:163], v[192:195], v[106:109]
	v_mfma_f32_16x16x32_bf16 v[94:97], v[152:155], v[204:207], v[94:97]
	v_mfma_f32_16x16x32_bf16 v[90:93], v[160:163], v[204:207], v[90:93]
	v_mfma_f32_16x16x32_bf16 v[78:81], v[152:155], v[212:215], v[78:81]
	v_mfma_f32_16x16x32_bf16 v[74:77], v[160:163], v[212:215], v[74:77]
	v_mfma_f32_16x16x32_bf16 v[126:129], v[156:159], v[188:191], v[126:129]
	v_mfma_f32_16x16x32_bf16 v[122:125], v[164:167], v[188:191], v[122:125]
	v_mfma_f32_16x16x32_bf16 v[110:113], v[156:159], v[196:199], v[110:113]
	v_mfma_f32_16x16x32_bf16 v[106:109], v[164:167], v[196:199], v[106:109]
	v_mfma_f32_16x16x32_bf16 v[94:97], v[156:159], v[208:211], v[94:97]
	v_mfma_f32_16x16x32_bf16 v[90:93], v[164:167], v[208:211], v[90:93]
	v_mfma_f32_16x16x32_bf16 v[78:81], v[156:159], v[216:219], v[78:81]
	v_mfma_f32_16x16x32_bf16 v[74:77], v[164:167], v[216:219], v[74:77]
	s_setprio 0
	s_setprio 1
	v_mfma_f32_16x16x32_bf16 v[118:121], v[168:171], v[184:187], v[118:121]
	v_mfma_f32_16x16x32_bf16 v[114:117], v[176:179], v[184:187], v[114:117]
	v_mfma_f32_16x16x32_bf16 v[102:105], v[168:171], v[192:195], v[102:105]
	v_mfma_f32_16x16x32_bf16 v[98:101], v[176:179], v[192:195], v[98:101]
	v_mfma_f32_16x16x32_bf16 v[86:89], v[168:171], v[204:207], v[86:89]
	v_mfma_f32_16x16x32_bf16 v[82:85], v[176:179], v[204:207], v[82:85]
	v_mfma_f32_16x16x32_bf16 v[70:73], v[168:171], v[212:215], v[70:73]
	v_mfma_f32_16x16x32_bf16 v[66:69], v[176:179], v[212:215], v[66:69]
	v_mfma_f32_16x16x32_bf16 v[118:121], v[172:175], v[188:191], v[118:121]
	v_mfma_f32_16x16x32_bf16 v[114:117], v[180:183], v[188:191], v[114:117]
	v_mfma_f32_16x16x32_bf16 v[102:105], v[172:175], v[196:199], v[102:105]
	v_mfma_f32_16x16x32_bf16 v[98:101], v[180:183], v[196:199], v[98:101]
	v_mfma_f32_16x16x32_bf16 v[86:89], v[172:175], v[208:211], v[86:89]
	v_mfma_f32_16x16x32_bf16 v[82:85], v[180:183], v[208:211], v[82:85]
	v_mfma_f32_16x16x32_bf16 v[70:73], v[172:175], v[216:219], v[70:73]
	v_mfma_f32_16x16x32_bf16 v[66:69], v[180:183], v[216:219], v[66:69]
	s_setprio 2
	s_barrier
	s_add_i32 s51, s42, s34
	v_lshl_add_u64 v[200:201], s[26:27], 0, v[132:133]
	s_mov_b32 m0, s51
	ds_read_b128 v[184:187], v150 offset:16384
	ds_read_b128 v[188:191], v150 offset:17408
	ds_read_b128 v[192:195], v150 offset:18432
	ds_read_b128 v[196:199], v150 offset:19456
	ds_read_b128 v[204:207], v150 offset:20480
	ds_read_b128 v[208:211], v150 offset:21504
	ds_read_b128 v[212:215], v150 offset:22528
	ds_read_b128 v[216:219], v150 offset:23552
	global_load_lds_dwordx4 v[200:201], off
	s_add_i32 m0, s51, 0x2000
	s_add_u32 s52, s26, 0x80000
	v_lshl_add_u64 v[220:221], s[26:27], 0, v[136:137]
	s_addc_u32 s53, s27, 0
	s_add_i32 s51, s43, s34
	global_load_lds_dwordx4 v[220:221], off
	v_lshl_add_u64 v[222:223], s[52:53], 0, v[132:133]
	s_mov_b32 m0, s51
	v_lshl_add_u64 v[224:225], s[28:29], 0, v[134:135]
	global_load_lds_dwordx4 v[222:223], off
	v_lshl_add_u64 v[222:223], s[52:53], 0, v[136:137]
	s_add_i32 m0, s51, 0x2000
	s_nop 0
	global_load_lds_dwordx4 v[222:223], off
	v_lshl_add_u64 v[222:223], s[28:29], 0, v[130:131]
	s_mov_b32 m0, s17
	s_nop 0
	global_load_lds_dwordx4 v[222:223], off
	s_mov_b32 m0, s35
	s_nop 0
	global_load_lds_dwordx4 v[224:225], off
	s_waitcnt vmcnt(8)
	s_waitcnt lgkmcnt(0)
	s_barrier
	s_setprio 1
	s_waitcnt lgkmcnt(0)
	v_mfma_f32_16x16x32_bf16 v[62:65], v[152:155], v[184:187], v[62:65]
	v_mfma_f32_16x16x32_bf16 v[58:61], v[160:163], v[184:187], v[58:61]
	v_mfma_f32_16x16x32_bf16 v[46:49], v[152:155], v[192:195], v[46:49]
	v_mfma_f32_16x16x32_bf16 v[42:45], v[160:163], v[192:195], v[42:45]
	v_mfma_f32_16x16x32_bf16 v[30:33], v[152:155], v[204:207], v[30:33]
	v_mfma_f32_16x16x32_bf16 v[26:29], v[160:163], v[204:207], v[26:29]
	v_mfma_f32_16x16x32_bf16 v[14:17], v[152:155], v[212:215], v[14:17]
	v_mfma_f32_16x16x32_bf16 v[10:13], v[160:163], v[212:215], v[10:13]
	v_mfma_f32_16x16x32_bf16 v[62:65], v[156:159], v[188:191], v[62:65]
	v_mfma_f32_16x16x32_bf16 v[58:61], v[164:167], v[188:191], v[58:61]
	v_mfma_f32_16x16x32_bf16 v[46:49], v[156:159], v[196:199], v[46:49]
	v_mfma_f32_16x16x32_bf16 v[42:45], v[164:167], v[196:199], v[42:45]
	v_mfma_f32_16x16x32_bf16 v[30:33], v[156:159], v[208:211], v[30:33]
	v_mfma_f32_16x16x32_bf16 v[26:29], v[164:167], v[208:211], v[26:29]
	v_mfma_f32_16x16x32_bf16 v[14:17], v[156:159], v[216:219], v[14:17]
	v_mfma_f32_16x16x32_bf16 v[10:13], v[164:167], v[216:219], v[10:13]
	s_setprio 0
	s_setprio 1
	v_mfma_f32_16x16x32_bf16 v[54:57], v[168:171], v[184:187], v[54:57]
	v_mfma_f32_16x16x32_bf16 v[50:53], v[176:179], v[184:187], v[50:53]
	v_mfma_f32_16x16x32_bf16 v[38:41], v[168:171], v[192:195], v[38:41]
	v_mfma_f32_16x16x32_bf16 v[34:37], v[176:179], v[192:195], v[34:37]
	v_mfma_f32_16x16x32_bf16 v[22:25], v[168:171], v[204:207], v[22:25]
	v_mfma_f32_16x16x32_bf16 v[18:21], v[176:179], v[204:207], v[18:21]
	v_mfma_f32_16x16x32_bf16 v[6:9], v[168:171], v[212:215], v[6:9]
	v_mfma_f32_16x16x32_bf16 v[2:5], v[176:179], v[212:215], v[2:5]
	v_mfma_f32_16x16x32_bf16 v[54:57], v[172:175], v[188:191], v[54:57]
	v_mfma_f32_16x16x32_bf16 v[50:53], v[180:183], v[188:191], v[50:53]
	v_mfma_f32_16x16x32_bf16 v[38:41], v[172:175], v[196:199], v[38:41]
	v_mfma_f32_16x16x32_bf16 v[34:37], v[180:183], v[196:199], v[34:37]
	v_mfma_f32_16x16x32_bf16 v[22:25], v[172:175], v[208:211], v[22:25]
	v_mfma_f32_16x16x32_bf16 v[18:21], v[180:183], v[208:211], v[18:21]
	v_mfma_f32_16x16x32_bf16 v[6:9], v[172:175], v[216:219], v[6:9]
	v_mfma_f32_16x16x32_bf16 v[2:5], v[180:183], v[216:219], v[2:5]
	s_setprio 2
	s_barrier
	s_add_i32 s51, 0, 0x18000
	v_add_u32_e32 v151, s51, v146
	s_add_i32 s52, 0, 0x1c000
	ds_read_b128 v[152:155], v151
	ds_read_b128 v[156:159], v151 offset:1024
	ds_read_b128 v[160:163], v151 offset:2048
	ds_read_b128 v[164:167], v151 offset:3072
	v_add_u32_e32 v151, s52, v146
	ds_read_b128 v[168:171], v151
	ds_read_b128 v[172:175], v151 offset:1024
	ds_read_b128 v[176:179], v151 offset:2048
	ds_read_b128 v[180:183], v151 offset:3072
	s_add_u32 s28, s28, 0x80000
	s_addc_u32 s29, s29, 0
	s_mov_b32 m0, s36
	v_lshl_add_u64 v[226:227], s[28:29], 0, v[130:131]
	ds_read_b128 v[184:187], v150 offset:32768
	ds_read_b128 v[188:191], v150 offset:33792
	ds_read_b128 v[192:195], v150 offset:34816
	ds_read_b128 v[196:199], v150 offset:35840
	ds_read_b128 v[204:207], v150 offset:36864
	ds_read_b128 v[208:211], v150 offset:37888
	ds_read_b128 v[212:215], v150 offset:38912
	ds_read_b128 v[216:219], v150 offset:39936
	global_load_lds_dwordx4 v[226:227], off
	v_lshl_add_u64 v[226:227], s[28:29], 0, v[134:135]
	s_mov_b32 m0, s37
	s_nop 0
	global_load_lds_dwordx4 v[226:227], off
	s_waitcnt vmcnt(8)
	s_waitcnt lgkmcnt(0)
	s_barrier
	s_setprio 1
	s_waitcnt lgkmcnt(0)
	v_mfma_f32_16x16x32_bf16 v[126:129], v[152:155], v[184:187], v[126:129]
	v_mfma_f32_16x16x32_bf16 v[122:125], v[160:163], v[184:187], v[122:125]
	v_mfma_f32_16x16x32_bf16 v[110:113], v[152:155], v[192:195], v[110:113]
	v_mfma_f32_16x16x32_bf16 v[106:109], v[160:163], v[192:195], v[106:109]
	v_mfma_f32_16x16x32_bf16 v[94:97], v[152:155], v[204:207], v[94:97]
	v_mfma_f32_16x16x32_bf16 v[90:93], v[160:163], v[204:207], v[90:93]
	v_mfma_f32_16x16x32_bf16 v[78:81], v[152:155], v[212:215], v[78:81]
	v_mfma_f32_16x16x32_bf16 v[74:77], v[160:163], v[212:215], v[74:77]
	v_mfma_f32_16x16x32_bf16 v[126:129], v[156:159], v[188:191], v[126:129]
	v_mfma_f32_16x16x32_bf16 v[122:125], v[164:167], v[188:191], v[122:125]
	v_mfma_f32_16x16x32_bf16 v[110:113], v[156:159], v[196:199], v[110:113]
	v_mfma_f32_16x16x32_bf16 v[106:109], v[164:167], v[196:199], v[106:109]
	v_mfma_f32_16x16x32_bf16 v[94:97], v[156:159], v[208:211], v[94:97]
	v_mfma_f32_16x16x32_bf16 v[90:93], v[164:167], v[208:211], v[90:93]
	v_mfma_f32_16x16x32_bf16 v[78:81], v[156:159], v[216:219], v[78:81]
	v_mfma_f32_16x16x32_bf16 v[74:77], v[164:167], v[216:219], v[74:77]
	s_setprio 0
	s_setprio 1
	v_mfma_f32_16x16x32_bf16 v[118:121], v[168:171], v[184:187], v[118:121]
	v_mfma_f32_16x16x32_bf16 v[114:117], v[176:179], v[184:187], v[114:117]
	v_mfma_f32_16x16x32_bf16 v[102:105], v[168:171], v[192:195], v[102:105]
	v_mfma_f32_16x16x32_bf16 v[98:101], v[176:179], v[192:195], v[98:101]
	v_mfma_f32_16x16x32_bf16 v[86:89], v[168:171], v[204:207], v[86:89]
	v_mfma_f32_16x16x32_bf16 v[82:85], v[176:179], v[204:207], v[82:85]
	v_mfma_f32_16x16x32_bf16 v[70:73], v[168:171], v[212:215], v[70:73]
	v_mfma_f32_16x16x32_bf16 v[66:69], v[176:179], v[212:215], v[66:69]
	v_mfma_f32_16x16x32_bf16 v[118:121], v[172:175], v[188:191], v[118:121]
	v_mfma_f32_16x16x32_bf16 v[114:117], v[180:183], v[188:191], v[114:117]
	v_mfma_f32_16x16x32_bf16 v[102:105], v[172:175], v[196:199], v[102:105]
	v_mfma_f32_16x16x32_bf16 v[98:101], v[180:183], v[196:199], v[98:101]
	v_mfma_f32_16x16x32_bf16 v[86:89], v[172:175], v[208:211], v[86:89]
	v_mfma_f32_16x16x32_bf16 v[82:85], v[180:183], v[208:211], v[82:85]
	v_mfma_f32_16x16x32_bf16 v[70:73], v[172:175], v[216:219], v[70:73]
	v_mfma_f32_16x16x32_bf16 v[66:69], v[180:183], v[216:219], v[66:69]
	s_setprio 2
	s_barrier
	s_add_i32 s28, s51, s34
	v_lshl_add_u64 v[200:201], v[200:201], 0, s[4:5]
	s_mov_b32 m0, s28
	ds_read_b128 v[184:187], v150 offset:49152
	ds_read_b128 v[188:191], v150 offset:50176
	ds_read_b128 v[192:195], v150 offset:51200
	ds_read_b128 v[196:199], v150 offset:52224
	ds_read_b128 v[204:207], v150 offset:53248
	ds_read_b128 v[208:211], v150 offset:54272
	ds_read_b128 v[212:215], v150 offset:55296
	ds_read_b128 v[216:219], v150 offset:56320
	global_load_lds_dwordx4 v[200:201], off
	s_add_i32 m0, s28, 0x2000
	s_add_u32 s26, s26, 0x80080
	v_lshl_add_u64 v[200:201], v[220:221], 0, s[4:5]
	s_addc_u32 s27, s27, 0
	s_add_i32 s28, s52, s34
	global_load_lds_dwordx4 v[200:201], off
	v_lshl_add_u64 v[200:201], s[26:27], 0, v[132:133]
	s_mov_b32 m0, s28
	s_nop 0
	global_load_lds_dwordx4 v[200:201], off
	v_lshl_add_u64 v[200:201], s[26:27], 0, v[136:137]
	s_add_i32 m0, s28, 0x2000
	s_nop 0
	global_load_lds_dwordx4 v[200:201], off
	v_lshl_add_u64 v[200:201], v[222:223], 0, s[4:5]
	s_mov_b32 m0, s39
	s_nop 0
	global_load_lds_dwordx4 v[200:201], off
	v_lshl_add_u64 v[200:201], v[224:225], 0, s[4:5]
	s_mov_b32 m0, s40
	s_nop 0
	global_load_lds_dwordx4 v[200:201], off
	s_waitcnt vmcnt(8)
	s_waitcnt lgkmcnt(0)
	s_barrier
	s_setprio 1
	s_waitcnt lgkmcnt(0)
	v_mfma_f32_16x16x32_bf16 v[62:65], v[152:155], v[184:187], v[62:65]
	v_mfma_f32_16x16x32_bf16 v[58:61], v[160:163], v[184:187], v[58:61]
	v_mfma_f32_16x16x32_bf16 v[46:49], v[152:155], v[192:195], v[46:49]
	v_mfma_f32_16x16x32_bf16 v[42:45], v[160:163], v[192:195], v[42:45]
	v_mfma_f32_16x16x32_bf16 v[30:33], v[152:155], v[204:207], v[30:33]
	v_mfma_f32_16x16x32_bf16 v[26:29], v[160:163], v[204:207], v[26:29]
	v_mfma_f32_16x16x32_bf16 v[14:17], v[152:155], v[212:215], v[14:17]
	v_mfma_f32_16x16x32_bf16 v[10:13], v[160:163], v[212:215], v[10:13]
	v_mfma_f32_16x16x32_bf16 v[62:65], v[156:159], v[188:191], v[62:65]
	v_mfma_f32_16x16x32_bf16 v[58:61], v[164:167], v[188:191], v[58:61]
	v_mfma_f32_16x16x32_bf16 v[46:49], v[156:159], v[196:199], v[46:49]
	v_mfma_f32_16x16x32_bf16 v[42:45], v[164:167], v[196:199], v[42:45]
	v_mfma_f32_16x16x32_bf16 v[30:33], v[156:159], v[208:211], v[30:33]
	v_mfma_f32_16x16x32_bf16 v[26:29], v[164:167], v[208:211], v[26:29]
	v_mfma_f32_16x16x32_bf16 v[14:17], v[156:159], v[216:219], v[14:17]
	v_mfma_f32_16x16x32_bf16 v[10:13], v[164:167], v[216:219], v[10:13]
	s_setprio 0
	s_setprio 1
	v_mfma_f32_16x16x32_bf16 v[54:57], v[168:171], v[184:187], v[54:57]
	v_mfma_f32_16x16x32_bf16 v[50:53], v[176:179], v[184:187], v[50:53]
	v_mfma_f32_16x16x32_bf16 v[38:41], v[168:171], v[192:195], v[38:41]
	v_mfma_f32_16x16x32_bf16 v[34:37], v[176:179], v[192:195], v[34:37]
	v_mfma_f32_16x16x32_bf16 v[22:25], v[168:171], v[204:207], v[22:25]
	v_mfma_f32_16x16x32_bf16 v[18:21], v[176:179], v[204:207], v[18:21]
	v_mfma_f32_16x16x32_bf16 v[6:9], v[168:171], v[212:215], v[6:9]
	v_mfma_f32_16x16x32_bf16 v[2:5], v[176:179], v[212:215], v[2:5]
	v_mfma_f32_16x16x32_bf16 v[54:57], v[172:175], v[188:191], v[54:57]
	v_mfma_f32_16x16x32_bf16 v[50:53], v[180:183], v[188:191], v[50:53]
	v_mfma_f32_16x16x32_bf16 v[38:41], v[172:175], v[196:199], v[38:41]
	v_mfma_f32_16x16x32_bf16 v[34:37], v[180:183], v[196:199], v[34:37]
	v_mfma_f32_16x16x32_bf16 v[22:25], v[172:175], v[208:211], v[22:25]
	v_mfma_f32_16x16x32_bf16 v[18:21], v[180:183], v[208:211], v[18:21]
	v_mfma_f32_16x16x32_bf16 v[6:9], v[172:175], v[216:219], v[6:9]
	v_mfma_f32_16x16x32_bf16 v[2:5], v[180:183], v[216:219], v[2:5]
	s_setprio 2
	s_barrier
	s_add_i32 s50, s50, 2
	s_add_u32 s24, s24, 0x100
	s_addc_u32 s25, s25, 0
	s_add_u32 s48, s48, 0x100
	s_addc_u32 s49, s49, 0
	s_cmp_gt_u32 s50, 29
	s_cbranch_scc0 .LBB0_203
	s_and_b64 vcc, exec, s[6:7]
	s_cbranch_vccz .LBB0_206
	s_barrier

.LBB0_285:
	ds_read_b128 v[130:133], v170
	ds_read_b128 v[134:137], v170 offset:1024
	ds_read_b128 v[138:141], v170 offset:2048
	ds_read_b128 v[142:145], v170 offset:3072
	ds_read_b128 v[158:161], v171
	ds_read_b128 v[162:165], v171 offset:1024
	ds_read_b128 v[174:177], v171 offset:2048
	ds_read_b128 v[178:181], v171 offset:3072
	s_add_u32 s26, s24, 0x100
	s_addc_u32 s27, s25, 0
	s_cmpk_eq_i32 s50, 0x54
	s_cselect_b32 s31, s3, s27
	s_cselect_b32 s30, s2, s26
	s_cselect_b32 s29, s23, s49
	s_cselect_b32 s28, s22, s48
	v_lshl_add_u64 v[166:167], s[24:25], 0, v[150:151]
	s_add_i32 m0, s33, 0xc000
	ds_read_b128 v[182:185], v172
	ds_read_b128 v[186:189], v172 offset:1024
	ds_read_b128 v[190:193], v172 offset:2048
	ds_read_b128 v[194:197], v172 offset:3072
	ds_read_b128 v[198:201], v172 offset:4096
	ds_read_b128 v[204:207], v172 offset:5120
	ds_read_b128 v[208:211], v172 offset:6144
	ds_read_b128 v[212:215], v172 offset:7168
	global_load_lds_dwordx4 v[166:167], off
	v_lshl_add_u64 v[166:167], s[24:25], 0, v[152:153]
	s_add_i32 m0, s33, 0xe000
	s_nop 0
	global_load_lds_dwordx4 v[166:167], off
	s_waitcnt vmcnt(8)
	s_waitcnt lgkmcnt(0)
	s_barrier
	s_setprio 1
	s_waitcnt lgkmcnt(0)
	v_mfma_f32_16x16x32_bf16 v[126:129], v[130:133], v[182:185], v[126:129]
	v_mfma_f32_16x16x32_bf16 v[122:125], v[138:141], v[182:185], v[122:125]
	v_mfma_f32_16x16x32_bf16 v[110:113], v[130:133], v[190:193], v[110:113]
	v_mfma_f32_16x16x32_bf16 v[106:109], v[138:141], v[190:193], v[106:109]
	v_mfma_f32_16x16x32_bf16 v[94:97], v[130:133], v[198:201], v[94:97]
	v_mfma_f32_16x16x32_bf16 v[90:93], v[138:141], v[198:201], v[90:93]
	v_mfma_f32_16x16x32_bf16 v[78:81], v[130:133], v[208:211], v[78:81]
	v_mfma_f32_16x16x32_bf16 v[74:77], v[138:141], v[208:211], v[74:77]
	v_mfma_f32_16x16x32_bf16 v[126:129], v[134:137], v[186:189], v[126:129]
	v_mfma_f32_16x16x32_bf16 v[122:125], v[142:145], v[186:189], v[122:125]
	v_mfma_f32_16x16x32_bf16 v[110:113], v[134:137], v[194:197], v[110:113]
	v_mfma_f32_16x16x32_bf16 v[106:109], v[142:145], v[194:197], v[106:109]
	v_mfma_f32_16x16x32_bf16 v[94:97], v[134:137], v[204:207], v[94:97]
	v_mfma_f32_16x16x32_bf16 v[90:93], v[142:145], v[204:207], v[90:93]
	v_mfma_f32_16x16x32_bf16 v[78:81], v[134:137], v[212:215], v[78:81]
	v_mfma_f32_16x16x32_bf16 v[74:77], v[142:145], v[212:215], v[74:77]
	s_setprio 0
	s_setprio 1
	v_mfma_f32_16x16x32_bf16 v[118:121], v[158:161], v[182:185], v[118:121]
	v_mfma_f32_16x16x32_bf16 v[114:117], v[174:177], v[182:185], v[114:117]
	v_mfma_f32_16x16x32_bf16 v[102:105], v[158:161], v[190:193], v[102:105]
	v_mfma_f32_16x16x32_bf16 v[98:101], v[174:177], v[190:193], v[98:101]
	v_mfma_f32_16x16x32_bf16 v[86:89], v[158:161], v[198:201], v[86:89]
	v_mfma_f32_16x16x32_bf16 v[82:85], v[174:177], v[198:201], v[82:85]
	v_mfma_f32_16x16x32_bf16 v[70:73], v[158:161], v[208:211], v[70:73]
	v_mfma_f32_16x16x32_bf16 v[66:69], v[174:177], v[208:211], v[66:69]
	v_mfma_f32_16x16x32_bf16 v[118:121], v[162:165], v[186:189], v[118:121]
	v_mfma_f32_16x16x32_bf16 v[114:117], v[178:181], v[186:189], v[114:117]
	v_mfma_f32_16x16x32_bf16 v[102:105], v[162:165], v[194:197], v[102:105]
	v_mfma_f32_16x16x32_bf16 v[98:101], v[178:181], v[194:197], v[98:101]
	v_mfma_f32_16x16x32_bf16 v[86:89], v[162:165], v[204:207], v[86:89]
	v_mfma_f32_16x16x32_bf16 v[82:85], v[178:181], v[204:207], v[82:85]
	v_mfma_f32_16x16x32_bf16 v[70:73], v[162:165], v[212:215], v[70:73]
	v_mfma_f32_16x16x32_bf16 v[66:69], v[178:181], v[212:215], v[66:69]
	s_setprio 2
	s_barrier
	s_add_i32 s24, s42, s17
	v_lshl_add_u64 v[166:167], s[28:29], 0, v[146:147]
	s_mov_b32 m0, s24
	ds_read_b128 v[182:185], v172 offset:16384
	ds_read_b128 v[186:189], v172 offset:17408
	ds_read_b128 v[190:193], v172 offset:18432
	ds_read_b128 v[194:197], v172 offset:19456
	ds_read_b128 v[198:201], v172 offset:20480
	ds_read_b128 v[204:207], v172 offset:21504
	ds_read_b128 v[208:211], v172 offset:22528
	ds_read_b128 v[212:215], v172 offset:23552
	global_load_lds_dwordx4 v[166:167], off
	s_add_i32 m0, s24, 0x2000
	s_add_u32 s24, s28, 0x160000
	v_lshl_add_u64 v[216:217], s[28:29], 0, v[148:149]
	s_addc_u32 s25, s29, 0
	s_add_i32 s51, s43, s17
	global_load_lds_dwordx4 v[216:217], off
	v_lshl_add_u64 v[218:219], s[24:25], 0, v[146:147]
	s_mov_b32 m0, s51
	v_lshl_add_u64 v[220:221], s[30:31], 0, v[148:149]
	global_load_lds_dwordx4 v[218:219], off
	v_lshl_add_u64 v[218:219], s[24:25], 0, v[148:149]
	s_add_i32 m0, s51, 0x2000
	s_nop 0
	global_load_lds_dwordx4 v[218:219], off
	v_lshl_add_u64 v[218:219], s[30:31], 0, v[146:147]
	s_mov_b32 m0, s33
	s_nop 0
	global_load_lds_dwordx4 v[218:219], off
	s_mov_b32 m0, s34
	s_nop 0
	global_load_lds_dwordx4 v[220:221], off
	s_waitcnt vmcnt(8)
	s_waitcnt lgkmcnt(0)
	s_barrier
	s_setprio 1
	s_waitcnt lgkmcnt(0)
	v_mfma_f32_16x16x32_bf16 v[62:65], v[130:133], v[182:185], v[62:65]
	v_mfma_f32_16x16x32_bf16 v[58:61], v[138:141], v[182:185], v[58:61]
	v_mfma_f32_16x16x32_bf16 v[46:49], v[130:133], v[190:193], v[46:49]
	v_mfma_f32_16x16x32_bf16 v[42:45], v[138:141], v[190:193], v[42:45]
	v_mfma_f32_16x16x32_bf16 v[30:33], v[130:133], v[198:201], v[30:33]
	v_mfma_f32_16x16x32_bf16 v[26:29], v[138:141], v[198:201], v[26:29]
	v_mfma_f32_16x16x32_bf16 v[14:17], v[130:133], v[208:211], v[14:17]
	v_mfma_f32_16x16x32_bf16 v[10:13], v[138:141], v[208:211], v[10:13]
	v_mfma_f32_16x16x32_bf16 v[62:65], v[134:137], v[186:189], v[62:65]
	v_mfma_f32_16x16x32_bf16 v[58:61], v[142:145], v[186:189], v[58:61]
	v_mfma_f32_16x16x32_bf16 v[46:49], v[134:137], v[194:197], v[46:49]
	v_mfma_f32_16x16x32_bf16 v[42:45], v[142:145], v[194:197], v[42:45]
	v_mfma_f32_16x16x32_bf16 v[30:33], v[134:137], v[204:207], v[30:33]
	v_mfma_f32_16x16x32_bf16 v[26:29], v[142:145], v[204:207], v[26:29]
	v_mfma_f32_16x16x32_bf16 v[14:17], v[134:137], v[212:215], v[14:17]
	v_mfma_f32_16x16x32_bf16 v[10:13], v[142:145], v[212:215], v[10:13]
	s_setprio 0
	s_setprio 1
	v_mfma_f32_16x16x32_bf16 v[54:57], v[158:161], v[182:185], v[54:57]
	v_mfma_f32_16x16x32_bf16 v[50:53], v[174:177], v[182:185], v[50:53]
	v_mfma_f32_16x16x32_bf16 v[38:41], v[158:161], v[190:193], v[38:41]
	v_mfma_f32_16x16x32_bf16 v[34:37], v[174:177], v[190:193], v[34:37]
	v_mfma_f32_16x16x32_bf16 v[22:25], v[158:161], v[198:201], v[22:25]
	v_mfma_f32_16x16x32_bf16 v[18:21], v[174:177], v[198:201], v[18:21]
	v_mfma_f32_16x16x32_bf16 v[6:9], v[158:161], v[208:211], v[6:9]
	v_mfma_f32_16x16x32_bf16 v[2:5], v[174:177], v[208:211], v[2:5]
	v_mfma_f32_16x16x32_bf16 v[54:57], v[162:165], v[186:189], v[54:57]
	v_mfma_f32_16x16x32_bf16 v[50:53], v[178:181], v[186:189], v[50:53]
	v_mfma_f32_16x16x32_bf16 v[38:41], v[162:165], v[194:197], v[38:41]
	v_mfma_f32_16x16x32_bf16 v[34:37], v[178:181], v[194:197], v[34:37]
	v_mfma_f32_16x16x32_bf16 v[22:25], v[162:165], v[204:207], v[22:25]
	v_mfma_f32_16x16x32_bf16 v[18:21], v[178:181], v[204:207], v[18:21]
	v_mfma_f32_16x16x32_bf16 v[6:9], v[162:165], v[212:215], v[6:9]
	v_mfma_f32_16x16x32_bf16 v[2:5], v[178:181], v[212:215], v[2:5]
	s_setprio 2
	s_barrier
	s_add_i32 s51, 0, 0x18000
	s_add_i32 s52, 0, 0x1c000
	v_add_u32_e32 v142, s51, v168
	v_add_u32_e32 v178, s52, v168
	ds_read_b128 v[130:133], v142
	ds_read_b128 v[134:137], v142 offset:1024
	ds_read_b128 v[138:141], v142 offset:2048
	ds_read_b128 v[142:145], v142 offset:3072
	ds_read_b128 v[158:161], v178
	ds_read_b128 v[162:165], v178 offset:1024
	ds_read_b128 v[174:177], v178 offset:2048
	ds_read_b128 v[178:181], v178 offset:3072
	s_add_u32 s24, s30, 0x160000
	s_addc_u32 s25, s31, 0
	s_mov_b32 m0, s35
	v_lshl_add_u64 v[222:223], s[24:25], 0, v[146:147]
	ds_read_b128 v[182:185], v172 offset:32768
	ds_read_b128 v[186:189], v172 offset:33792
	ds_read_b128 v[190:193], v172 offset:34816
	ds_read_b128 v[194:197], v172 offset:35840
	ds_read_b128 v[198:201], v172 offset:36864
	ds_read_b128 v[204:207], v172 offset:37888
	ds_read_b128 v[208:211], v172 offset:38912
	ds_read_b128 v[212:215], v172 offset:39936
	global_load_lds_dwordx4 v[222:223], off
	v_lshl_add_u64 v[222:223], s[24:25], 0, v[148:149]
	s_mov_b32 m0, s36
	s_nop 0
	global_load_lds_dwordx4 v[222:223], off
	s_waitcnt vmcnt(8)
	s_waitcnt lgkmcnt(0)
	s_barrier
	s_setprio 1
	s_waitcnt lgkmcnt(0)
	v_mfma_f32_16x16x32_bf16 v[126:129], v[130:133], v[182:185], v[126:129]
	v_mfma_f32_16x16x32_bf16 v[122:125], v[138:141], v[182:185], v[122:125]
	v_mfma_f32_16x16x32_bf16 v[110:113], v[130:133], v[190:193], v[110:113]
	v_mfma_f32_16x16x32_bf16 v[106:109], v[138:141], v[190:193], v[106:109]
	v_mfma_f32_16x16x32_bf16 v[94:97], v[130:133], v[198:201], v[94:97]
	v_mfma_f32_16x16x32_bf16 v[90:93], v[138:141], v[198:201], v[90:93]
	v_mfma_f32_16x16x32_bf16 v[78:81], v[130:133], v[208:211], v[78:81]
	v_mfma_f32_16x16x32_bf16 v[74:77], v[138:141], v[208:211], v[74:77]
	v_mfma_f32_16x16x32_bf16 v[126:129], v[134:137], v[186:189], v[126:129]
	v_mfma_f32_16x16x32_bf16 v[122:125], v[142:145], v[186:189], v[122:125]
	v_mfma_f32_16x16x32_bf16 v[110:113], v[134:137], v[194:197], v[110:113]
	v_mfma_f32_16x16x32_bf16 v[106:109], v[142:145], v[194:197], v[106:109]
	v_mfma_f32_16x16x32_bf16 v[94:97], v[134:137], v[204:207], v[94:97]
	v_mfma_f32_16x16x32_bf16 v[90:93], v[142:145], v[204:207], v[90:93]
	v_mfma_f32_16x16x32_bf16 v[78:81], v[134:137], v[212:215], v[78:81]
	v_mfma_f32_16x16x32_bf16 v[74:77], v[142:145], v[212:215], v[74:77]
	s_setprio 0
	s_setprio 1
	v_mfma_f32_16x16x32_bf16 v[118:121], v[158:161], v[182:185], v[118:121]
	v_mfma_f32_16x16x32_bf16 v[114:117], v[174:177], v[182:185], v[114:117]
	v_mfma_f32_16x16x32_bf16 v[102:105], v[158:161], v[190:193], v[102:105]
	v_mfma_f32_16x16x32_bf16 v[98:101], v[174:177], v[190:193], v[98:101]
	v_mfma_f32_16x16x32_bf16 v[86:89], v[158:161], v[198:201], v[86:89]
	v_mfma_f32_16x16x32_bf16 v[82:85], v[174:177], v[198:201], v[82:85]
	v_mfma_f32_16x16x32_bf16 v[70:73], v[158:161], v[208:211], v[70:73]
	v_mfma_f32_16x16x32_bf16 v[66:69], v[174:177], v[208:211], v[66:69]
	v_mfma_f32_16x16x32_bf16 v[118:121], v[162:165], v[186:189], v[118:121]
	v_mfma_f32_16x16x32_bf16 v[114:117], v[178:181], v[186:189], v[114:117]
	v_mfma_f32_16x16x32_bf16 v[102:105], v[162:165], v[194:197], v[102:105]
	v_mfma_f32_16x16x32_bf16 v[98:101], v[178:181], v[194:197], v[98:101]
	v_mfma_f32_16x16x32_bf16 v[86:89], v[162:165], v[204:207], v[86:89]
	v_mfma_f32_16x16x32_bf16 v[82:85], v[178:181], v[204:207], v[82:85]
	v_mfma_f32_16x16x32_bf16 v[70:73], v[162:165], v[212:215], v[70:73]
	v_mfma_f32_16x16x32_bf16 v[66:69], v[178:181], v[212:215], v[66:69]
	s_setprio 2
	s_barrier
	s_add_i32 s24, s51, s17
	v_lshl_add_u64 v[166:167], v[166:167], 0, s[8:9]
	s_mov_b32 m0, s24
	ds_read_b128 v[182:185], v172 offset:49152
	ds_read_b128 v[186:189], v172 offset:50176
	ds_read_b128 v[190:193], v172 offset:51200
	ds_read_b128 v[194:197], v172 offset:52224
	ds_read_b128 v[198:201], v172 offset:53248
	ds_read_b128 v[204:207], v172 offset:54272
	ds_read_b128 v[208:211], v172 offset:55296
	ds_read_b128 v[212:215], v172 offset:56320
	global_load_lds_dwordx4 v[166:167], off
	s_add_i32 m0, s24, 0x2000
	s_add_u32 s24, s28, 0x160080
	v_lshl_add_u64 v[166:167], v[216:217], 0, s[8:9]
	s_addc_u32 s25, s29, 0
	s_add_i32 s28, s52, s17
	global_load_lds_dwordx4 v[166:167], off
	v_lshl_add_u64 v[166:167], s[24:25], 0, v[146:147]
	s_mov_b32 m0, s28
	s_nop 0
	global_load_lds_dwordx4 v[166:167], off
	v_lshl_add_u64 v[166:167], s[24:25], 0, v[148:149]
	s_add_i32 m0, s28, 0x2000
	s_nop 0
	global_load_lds_dwordx4 v[166:167], off
	v_lshl_add_u64 v[166:167], v[218:219], 0, s[8:9]
	s_mov_b32 m0, s38
	s_nop 0
	global_load_lds_dwordx4 v[166:167], off
	v_lshl_add_u64 v[166:167], v[220:221], 0, s[8:9]
	s_mov_b32 m0, s39
	s_nop 0
	global_load_lds_dwordx4 v[166:167], off
	s_waitcnt vmcnt(8)
	s_waitcnt lgkmcnt(0)
	s_barrier
	s_setprio 1
	s_waitcnt lgkmcnt(0)
	v_mfma_f32_16x16x32_bf16 v[62:65], v[130:133], v[182:185], v[62:65]
	v_mfma_f32_16x16x32_bf16 v[58:61], v[138:141], v[182:185], v[58:61]
	v_mfma_f32_16x16x32_bf16 v[46:49], v[130:133], v[190:193], v[46:49]
	v_mfma_f32_16x16x32_bf16 v[42:45], v[138:141], v[190:193], v[42:45]
	v_mfma_f32_16x16x32_bf16 v[30:33], v[130:133], v[198:201], v[30:33]
	v_mfma_f32_16x16x32_bf16 v[26:29], v[138:141], v[198:201], v[26:29]
	v_mfma_f32_16x16x32_bf16 v[14:17], v[130:133], v[208:211], v[14:17]
	v_mfma_f32_16x16x32_bf16 v[10:13], v[138:141], v[208:211], v[10:13]
	v_mfma_f32_16x16x32_bf16 v[62:65], v[134:137], v[186:189], v[62:65]
	v_mfma_f32_16x16x32_bf16 v[58:61], v[142:145], v[186:189], v[58:61]
	v_mfma_f32_16x16x32_bf16 v[46:49], v[134:137], v[194:197], v[46:49]
	v_mfma_f32_16x16x32_bf16 v[42:45], v[142:145], v[194:197], v[42:45]
	v_mfma_f32_16x16x32_bf16 v[30:33], v[134:137], v[204:207], v[30:33]
	v_mfma_f32_16x16x32_bf16 v[26:29], v[142:145], v[204:207], v[26:29]
	v_mfma_f32_16x16x32_bf16 v[14:17], v[134:137], v[212:215], v[14:17]
	v_mfma_f32_16x16x32_bf16 v[10:13], v[142:145], v[212:215], v[10:13]
	s_setprio 0
	s_setprio 1
	v_mfma_f32_16x16x32_bf16 v[54:57], v[158:161], v[182:185], v[54:57]
	v_mfma_f32_16x16x32_bf16 v[50:53], v[174:177], v[182:185], v[50:53]
	v_mfma_f32_16x16x32_bf16 v[38:41], v[158:161], v[190:193], v[38:41]
	v_mfma_f32_16x16x32_bf16 v[34:37], v[174:177], v[190:193], v[34:37]
	v_mfma_f32_16x16x32_bf16 v[22:25], v[158:161], v[198:201], v[22:25]
	v_mfma_f32_16x16x32_bf16 v[18:21], v[174:177], v[198:201], v[18:21]
	v_mfma_f32_16x16x32_bf16 v[6:9], v[158:161], v[208:211], v[6:9]
	v_mfma_f32_16x16x32_bf16 v[2:5], v[174:177], v[208:211], v[2:5]
	v_mfma_f32_16x16x32_bf16 v[54:57], v[162:165], v[186:189], v[54:57]
	v_mfma_f32_16x16x32_bf16 v[50:53], v[178:181], v[186:189], v[50:53]
	v_mfma_f32_16x16x32_bf16 v[38:41], v[162:165], v[194:197], v[38:41]
	v_mfma_f32_16x16x32_bf16 v[34:37], v[178:181], v[194:197], v[34:37]
	v_mfma_f32_16x16x32_bf16 v[22:25], v[162:165], v[204:207], v[22:25]
	v_mfma_f32_16x16x32_bf16 v[18:21], v[178:181], v[204:207], v[18:21]
	v_mfma_f32_16x16x32_bf16 v[6:9], v[162:165], v[212:215], v[6:9]
	v_mfma_f32_16x16x32_bf16 v[2:5], v[178:181], v[212:215], v[2:5]
	s_setprio 2
	s_barrier
	s_add_i32 s50, s50, 2
	s_add_u32 s48, s48, 0x100
	s_addc_u32 s49, s49, 0
	s_cmpk_gt_u32 s50, 0x55
	s_mov_b64 s[24:25], s[26:27]
	s_cbranch_scc0 .LBB0_285
	s_and_b64 vcc, exec, s[10:11]
	s_cbranch_vccz .LBB0_288
	s_barrier

.LBB0_387:
	ds_read_b128 v[18:21], v219
	ds_read_b128 v[22:25], v219 offset:1024
	ds_read_b128 v[26:29], v219 offset:2048
	ds_read_b128 v[30:33], v219 offset:3072
	ds_read_b128 v[34:37], v220
	ds_read_b128 v[38:41], v220 offset:1024
	ds_read_b128 v[42:45], v220 offset:2048
	ds_read_b128 v[46:49], v220 offset:3072
	s_add_u32 s10, s2, 0xfff80080
	s_addc_u32 s11, s3, -1
	s_cmp_eq_u32 s23, 28
	s_cselect_b32 s13, s1, s11
	s_cselect_b32 s12, s15, s10
	s_cselect_b32 s11, s16, s19
	s_cselect_b32 s10, s17, s18
	v_lshl_add_u64 v[200:201], s[2:3], 0, v[192:193]
	s_add_i32 m0, s47, 0xc000
	ds_read_b128 v[114:117], v221
	ds_read_b128 v[150:153], v221 offset:1024
	ds_read_b128 v[170:173], v221 offset:2048
	ds_read_b128 v[174:177], v221 offset:3072
	ds_read_b128 v[178:181], v221 offset:4096
	ds_read_b128 v[228:231], v221 offset:5120
	ds_read_b128 v[232:235], v221 offset:6144
	ds_read_b128 v[236:239], v221 offset:7168
	global_load_lds_dwordx4 v[200:201], off
	v_lshl_add_u64 v[200:201], s[2:3], 0, v[194:195]
	s_add_i32 m0, s47, 0xe000
	s_nop 0
	global_load_lds_dwordx4 v[200:201], off
	s_waitcnt vmcnt(8)
	s_waitcnt lgkmcnt(0)
	s_barrier
	s_setprio 1
	s_waitcnt lgkmcnt(0)
	v_mfma_f32_16x16x32_bf16 v[166:169], v[18:21], v[114:117], v[166:169]
	v_mfma_f32_16x16x32_bf16 v[162:165], v[26:29], v[114:117], v[162:165]
	v_mfma_f32_16x16x32_bf16 v[146:149], v[18:21], v[170:173], v[146:149]
	v_mfma_f32_16x16x32_bf16 v[142:145], v[26:29], v[170:173], v[142:145]
	v_mfma_f32_16x16x32_bf16 v[130:133], v[18:21], v[178:181], v[130:133]
	v_mfma_f32_16x16x32_bf16 v[126:129], v[26:29], v[178:181], v[126:129]
	v_mfma_f32_16x16x32_bf16 v[110:113], v[18:21], v[232:235], v[110:113]
	v_mfma_f32_16x16x32_bf16 v[106:109], v[26:29], v[232:235], v[106:109]
	v_mfma_f32_16x16x32_bf16 v[166:169], v[22:25], v[150:153], v[166:169]
	v_mfma_f32_16x16x32_bf16 v[162:165], v[30:33], v[150:153], v[162:165]
	v_mfma_f32_16x16x32_bf16 v[146:149], v[22:25], v[174:177], v[146:149]
	v_mfma_f32_16x16x32_bf16 v[142:145], v[30:33], v[174:177], v[142:145]
	v_mfma_f32_16x16x32_bf16 v[130:133], v[22:25], v[228:231], v[130:133]
	v_mfma_f32_16x16x32_bf16 v[126:129], v[30:33], v[228:231], v[126:129]
	v_mfma_f32_16x16x32_bf16 v[110:113], v[22:25], v[236:239], v[110:113]
	v_mfma_f32_16x16x32_bf16 v[106:109], v[30:33], v[236:239], v[106:109]
	s_setprio 0
	s_setprio 1
	v_mfma_f32_16x16x32_bf16 v[158:161], v[34:37], v[114:117], v[158:161]
	v_mfma_f32_16x16x32_bf16 v[138:141], v[34:37], v[170:173], v[138:141]
	v_mfma_f32_16x16x32_bf16 v[134:137], v[42:45], v[170:173], v[134:137]
	v_mfma_f32_16x16x32_bf16 v[122:125], v[34:37], v[178:181], v[122:125]
	v_mfma_f32_16x16x32_bf16 v[118:121], v[42:45], v[178:181], v[118:121]
	v_mfma_f32_16x16x32_bf16 v[102:105], v[34:37], v[232:235], v[102:105]
	v_mfma_f32_16x16x32_bf16 v[98:101], v[42:45], v[232:235], v[98:101]
	v_mfma_f32_16x16x32_bf16 v[158:161], v[38:41], v[150:153], v[158:161]
	v_mfma_f32_16x16x32_bf16 v[114:117], v[42:45], v[114:117], v[154:157]
	v_mfma_f32_16x16x32_bf16 v[138:141], v[38:41], v[174:177], v[138:141]
	v_mfma_f32_16x16x32_bf16 v[134:137], v[46:49], v[174:177], v[134:137]
	v_mfma_f32_16x16x32_bf16 v[122:125], v[38:41], v[228:231], v[122:125]
	v_mfma_f32_16x16x32_bf16 v[118:121], v[46:49], v[228:231], v[118:121]
	v_mfma_f32_16x16x32_bf16 v[102:105], v[38:41], v[236:239], v[102:105]
	v_mfma_f32_16x16x32_bf16 v[98:101], v[46:49], v[236:239], v[98:101]
	v_mfma_f32_16x16x32_bf16 v[114:117], v[46:49], v[150:153], v[114:117]
	s_setprio 2
	s_barrier
	s_add_i32 s33, s84, s43
	v_lshl_add_u64 v[200:201], s[10:11], 0, v[182:183]
	s_mov_b32 m0, s33
	ds_read_b128 v[150:153], v221 offset:16384
	ds_read_b128 v[154:157], v221 offset:17408
	ds_read_b128 v[170:173], v221 offset:18432
	ds_read_b128 v[174:177], v221 offset:19456
	ds_read_b128 v[178:181], v221 offset:20480
	ds_read_b128 v[228:231], v221 offset:21504
	ds_read_b128 v[232:235], v221 offset:22528
	ds_read_b128 v[236:239], v221 offset:23552
	global_load_lds_dwordx4 v[200:201], off
	s_add_i32 m0, s33, 0x2000
	s_add_u32 s60, s10, 0x80000
	v_lshl_add_u64 v[248:249], s[10:11], 0, v[184:185]
	s_addc_u32 s61, s11, 0
	s_add_i32 s33, s85, s43
	global_load_lds_dwordx4 v[248:249], off
	v_lshl_add_u64 v[240:241], s[60:61], 0, v[182:183]
	s_mov_b32 m0, s33
	v_lshl_add_u64 v[250:251], s[12:13], 0, v[182:183]
	global_load_lds_dwordx4 v[240:241], off
	v_lshl_add_u64 v[240:241], s[60:61], 0, v[184:185]
	s_add_i32 m0, s33, 0x2000
	v_lshl_add_u64 v[210:211], s[12:13], 0, v[184:185]
	global_load_lds_dwordx4 v[240:241], off
	s_mov_b32 m0, s47
	s_nop 0
	global_load_lds_dwordx4 v[250:251], off
	s_mov_b32 m0, s51
	s_nop 0
	global_load_lds_dwordx4 v[210:211], off
	s_waitcnt vmcnt(8)
	s_waitcnt lgkmcnt(0)
	s_barrier
	s_setprio 1
	s_waitcnt lgkmcnt(0)
	v_mfma_f32_16x16x32_bf16 v[94:97], v[18:21], v[150:153], v[94:97]
	v_mfma_f32_16x16x32_bf16 v[90:93], v[26:29], v[150:153], v[90:93]
	v_mfma_f32_16x16x32_bf16 v[78:81], v[18:21], v[170:173], v[78:81]
	v_mfma_f32_16x16x32_bf16 v[74:77], v[26:29], v[170:173], v[74:77]
	v_mfma_f32_16x16x32_bf16 v[62:65], v[18:21], v[178:181], v[62:65]
	v_mfma_f32_16x16x32_bf16 v[58:61], v[26:29], v[178:181], v[58:61]
	v_mfma_f32_16x16x32_bf16 v[14:17], v[18:21], v[232:235], v[14:17]
	v_mfma_f32_16x16x32_bf16 v[10:13], v[26:29], v[232:235], v[10:13]
	v_mfma_f32_16x16x32_bf16 v[94:97], v[22:25], v[154:157], v[94:97]
	v_mfma_f32_16x16x32_bf16 v[90:93], v[30:33], v[154:157], v[90:93]
	v_mfma_f32_16x16x32_bf16 v[78:81], v[22:25], v[174:177], v[78:81]
	v_mfma_f32_16x16x32_bf16 v[74:77], v[30:33], v[174:177], v[74:77]
	v_mfma_f32_16x16x32_bf16 v[62:65], v[22:25], v[228:231], v[62:65]
	v_mfma_f32_16x16x32_bf16 v[58:61], v[30:33], v[228:231], v[58:61]
	v_mfma_f32_16x16x32_bf16 v[14:17], v[22:25], v[236:239], v[14:17]
	v_mfma_f32_16x16x32_bf16 v[10:13], v[30:33], v[236:239], v[10:13]
	s_setprio 0
	s_setprio 1
	v_mfma_f32_16x16x32_bf16 v[54:57], v[34:37], v[178:181], v[54:57]
	v_mfma_f32_16x16x32_bf16 v[50:53], v[42:45], v[178:181], v[50:53]
	v_mfma_f32_16x16x32_bf16 v[6:9], v[34:37], v[232:235], v[6:9]
	v_mfma_f32_16x16x32_bf16 v[2:5], v[42:45], v[232:235], v[2:5]
	v_mfma_f32_16x16x32_bf16 v[18:21], v[34:37], v[150:153], v[86:89]
	v_mfma_f32_16x16x32_bf16 v[22:25], v[42:45], v[150:153], v[82:85]
	v_mfma_f32_16x16x32_bf16 v[26:29], v[34:37], v[170:173], v[70:73]
	v_mfma_f32_16x16x32_bf16 v[30:33], v[42:45], v[170:173], v[66:69]
	v_mfma_f32_16x16x32_bf16 v[54:57], v[38:41], v[228:231], v[54:57]
	v_mfma_f32_16x16x32_bf16 v[50:53], v[46:49], v[228:231], v[50:53]
	v_mfma_f32_16x16x32_bf16 v[6:9], v[38:41], v[236:239], v[6:9]
	v_mfma_f32_16x16x32_bf16 v[2:5], v[46:49], v[236:239], v[2:5]
	v_mfma_f32_16x16x32_bf16 v[18:21], v[38:41], v[154:157], v[18:21]
	v_mfma_f32_16x16x32_bf16 v[22:25], v[46:49], v[154:157], v[22:25]
	v_mfma_f32_16x16x32_bf16 v[26:29], v[38:41], v[174:177], v[26:29]
	v_mfma_f32_16x16x32_bf16 v[30:33], v[46:49], v[174:177], v[30:33]
	s_setprio 2
	s_barrier
	s_add_i32 s33, 0, 0x18000
	s_add_i32 s46, 0, 0x1c000
	v_add_u32_e32 v46, s33, v204
	v_add_u32_e32 v66, s46, v204
	ds_read_b128 v[34:37], v46
	ds_read_b128 v[38:41], v46 offset:1024
	ds_read_b128 v[42:45], v46 offset:2048
	ds_read_b128 v[46:49], v46 offset:3072
	ds_read_b128 v[150:153], v66
	ds_read_b128 v[170:173], v66 offset:1024
	ds_read_b128 v[174:177], v66 offset:2048
	ds_read_b128 v[178:181], v66 offset:3072
	s_add_u32 s12, s12, 0x80000
	s_addc_u32 s13, s13, 0
	s_mov_b32 m0, s74
	v_lshl_add_u64 v[154:155], s[12:13], 0, v[182:183]
	ds_read_b128 v[66:69], v221 offset:32768
	ds_read_b128 v[70:73], v221 offset:33792
	ds_read_b128 v[82:85], v221 offset:34816
	ds_read_b128 v[86:89], v221 offset:35840
	ds_read_b128 v[228:231], v221 offset:36864
	ds_read_b128 v[232:235], v221 offset:37888
	ds_read_b128 v[236:239], v221 offset:38912
	ds_read_b128 v[240:243], v221 offset:39936
	global_load_lds_dwordx4 v[154:155], off
	v_lshl_add_u64 v[154:155], s[12:13], 0, v[184:185]
	s_mov_b32 m0, s75
	s_nop 0
	global_load_lds_dwordx4 v[154:155], off
	s_waitcnt vmcnt(8)
	s_waitcnt lgkmcnt(0)
	s_barrier
	s_setprio 1
	s_waitcnt lgkmcnt(0)
	v_mfma_f32_16x16x32_bf16 v[154:157], v[34:37], v[66:69], v[166:169]
	v_mfma_f32_16x16x32_bf16 v[166:169], v[38:41], v[70:73], v[154:157]
	v_mfma_f32_16x16x32_bf16 v[154:157], v[42:45], v[66:69], v[162:165]
	v_mfma_f32_16x16x32_bf16 v[146:149], v[34:37], v[82:85], v[146:149]
	v_mfma_f32_16x16x32_bf16 v[142:145], v[42:45], v[82:85], v[142:145]
	v_mfma_f32_16x16x32_bf16 v[130:133], v[34:37], v[228:231], v[130:133]
	v_mfma_f32_16x16x32_bf16 v[126:129], v[42:45], v[228:231], v[126:129]
	v_mfma_f32_16x16x32_bf16 v[110:113], v[34:37], v[236:239], v[110:113]
	v_mfma_f32_16x16x32_bf16 v[106:109], v[42:45], v[236:239], v[106:109]
	v_mfma_f32_16x16x32_bf16 v[162:165], v[46:49], v[70:73], v[154:157]
	v_mfma_f32_16x16x32_bf16 v[146:149], v[38:41], v[86:89], v[146:149]
	v_mfma_f32_16x16x32_bf16 v[142:145], v[46:49], v[86:89], v[142:145]
	v_mfma_f32_16x16x32_bf16 v[130:133], v[38:41], v[232:235], v[130:133]
	v_mfma_f32_16x16x32_bf16 v[126:129], v[46:49], v[232:235], v[126:129]
	v_mfma_f32_16x16x32_bf16 v[110:113], v[38:41], v[240:243], v[110:113]
	v_mfma_f32_16x16x32_bf16 v[106:109], v[46:49], v[240:243], v[106:109]
	s_setprio 0
	s_setprio 1
	v_mfma_f32_16x16x32_bf16 v[154:157], v[150:153], v[66:69], v[158:161]
	v_mfma_f32_16x16x32_bf16 v[66:69], v[174:177], v[66:69], v[114:117]
	v_mfma_f32_16x16x32_bf16 v[158:161], v[170:173], v[70:73], v[154:157]
	v_mfma_f32_16x16x32_bf16 v[154:157], v[178:181], v[70:73], v[66:69]
	v_mfma_f32_16x16x32_bf16 v[66:69], v[150:153], v[82:85], v[138:141]
	v_mfma_f32_16x16x32_bf16 v[138:141], v[170:173], v[86:89], v[66:69]
	v_mfma_f32_16x16x32_bf16 v[66:69], v[174:177], v[82:85], v[134:137]
	v_mfma_f32_16x16x32_bf16 v[134:137], v[178:181], v[86:89], v[66:69]
	v_mfma_f32_16x16x32_bf16 v[66:69], v[150:153], v[228:231], v[122:125]
	v_mfma_f32_16x16x32_bf16 v[122:125], v[170:173], v[232:235], v[66:69]
	v_mfma_f32_16x16x32_bf16 v[66:69], v[174:177], v[228:231], v[118:121]
	v_mfma_f32_16x16x32_bf16 v[118:121], v[178:181], v[232:235], v[66:69]
	v_mfma_f32_16x16x32_bf16 v[66:69], v[150:153], v[236:239], v[102:105]
	v_mfma_f32_16x16x32_bf16 v[102:105], v[170:173], v[240:243], v[66:69]
	v_mfma_f32_16x16x32_bf16 v[66:69], v[174:177], v[236:239], v[98:101]
	v_mfma_f32_16x16x32_bf16 v[98:101], v[178:181], v[240:243], v[66:69]
	s_setprio 2
	s_barrier
	s_add_i32 s12, s33, s43
	v_lshl_add_u64 v[82:83], v[200:201], 0, s[28:29]
	s_mov_b32 m0, s12
	s_nop 1
	ds_read_b128 v[66:69], v221 offset:49152
	ds_read_b128 v[70:73], v221 offset:50176
	ds_read_b128 v[114:117], v221 offset:51200
	ds_read_b128 v[228:231], v221 offset:52224
	ds_read_b128 v[232:235], v221 offset:53248
	ds_read_b128 v[236:239], v221 offset:54272
	ds_read_b128 v[240:243], v221 offset:55296
	ds_read_b128 v[244:247], v221 offset:56320
	global_load_lds_dwordx4 v[82:83], off
	s_add_i32 m0, s12, 0x2000
	s_add_u32 s10, s10, 0x80080
	v_lshl_add_u64 v[82:83], v[248:249], 0, s[28:29]
	s_addc_u32 s11, s11, 0
	s_add_i32 s12, s46, s43
	global_load_lds_dwordx4 v[82:83], off
	v_lshl_add_u64 v[82:83], s[10:11], 0, v[182:183]
	s_mov_b32 m0, s12
	s_nop 0
	global_load_lds_dwordx4 v[82:83], off
	v_lshl_add_u64 v[82:83], s[10:11], 0, v[184:185]
	s_add_i32 m0, s12, 0x2000
	s_nop 0
	global_load_lds_dwordx4 v[82:83], off
	v_lshl_add_u64 v[82:83], v[250:251], 0, s[28:29]
	s_mov_b32 m0, s77
	s_nop 0
	global_load_lds_dwordx4 v[82:83], off
	v_lshl_add_u64 v[82:83], v[210:211], 0, s[28:29]
	s_mov_b32 m0, s78
	s_nop 0
	global_load_lds_dwordx4 v[82:83], off
	s_waitcnt vmcnt(8)
	s_waitcnt lgkmcnt(0)
	s_barrier
	s_setprio 1
	s_waitcnt lgkmcnt(0)
	v_mfma_f32_16x16x32_bf16 v[82:85], v[34:37], v[66:69], v[94:97]
	v_mfma_f32_16x16x32_bf16 v[94:97], v[38:41], v[70:73], v[82:85]
	v_mfma_f32_16x16x32_bf16 v[82:85], v[42:45], v[66:69], v[90:93]
	v_mfma_f32_16x16x32_bf16 v[78:81], v[34:37], v[114:117], v[78:81]
	v_mfma_f32_16x16x32_bf16 v[74:77], v[42:45], v[114:117], v[74:77]
	v_mfma_f32_16x16x32_bf16 v[62:65], v[34:37], v[232:235], v[62:65]
	v_mfma_f32_16x16x32_bf16 v[58:61], v[42:45], v[232:235], v[58:61]
	v_mfma_f32_16x16x32_bf16 v[14:17], v[34:37], v[240:243], v[14:17]
	v_mfma_f32_16x16x32_bf16 v[10:13], v[42:45], v[240:243], v[10:13]
	v_mfma_f32_16x16x32_bf16 v[90:93], v[46:49], v[70:73], v[82:85]
	v_mfma_f32_16x16x32_bf16 v[78:81], v[38:41], v[228:231], v[78:81]
	v_mfma_f32_16x16x32_bf16 v[74:77], v[46:49], v[228:231], v[74:77]
	v_mfma_f32_16x16x32_bf16 v[62:65], v[38:41], v[236:239], v[62:65]
	v_mfma_f32_16x16x32_bf16 v[58:61], v[46:49], v[236:239], v[58:61]
	v_mfma_f32_16x16x32_bf16 v[14:17], v[38:41], v[244:247], v[14:17]
	v_mfma_f32_16x16x32_bf16 v[10:13], v[46:49], v[244:247], v[10:13]
	s_setprio 0
	s_setprio 1
	v_mfma_f32_16x16x32_bf16 v[18:21], v[150:153], v[66:69], v[18:21]
	v_mfma_f32_16x16x32_bf16 v[86:89], v[170:173], v[70:73], v[18:21]
	v_mfma_f32_16x16x32_bf16 v[18:21], v[174:177], v[66:69], v[22:25]
	v_mfma_f32_16x16x32_bf16 v[82:85], v[178:181], v[70:73], v[18:21]
	v_mfma_f32_16x16x32_bf16 v[18:21], v[150:153], v[114:117], v[26:29]
	v_mfma_f32_16x16x32_bf16 v[70:73], v[170:173], v[228:231], v[18:21]
	v_mfma_f32_16x16x32_bf16 v[18:21], v[174:177], v[114:117], v[30:33]
	v_mfma_f32_16x16x32_bf16 v[66:69], v[178:181], v[228:231], v[18:21]
	v_mfma_f32_16x16x32_bf16 v[18:21], v[150:153], v[232:235], v[54:57]
	v_mfma_f32_16x16x32_bf16 v[54:57], v[170:173], v[236:239], v[18:21]
	v_mfma_f32_16x16x32_bf16 v[18:21], v[174:177], v[232:235], v[50:53]
	v_mfma_f32_16x16x32_bf16 v[6:9], v[150:153], v[240:243], v[6:9]
	v_mfma_f32_16x16x32_bf16 v[2:5], v[174:177], v[240:243], v[2:5]
	v_mfma_f32_16x16x32_bf16 v[50:53], v[178:181], v[236:239], v[18:21]
	v_mfma_f32_16x16x32_bf16 v[6:9], v[170:173], v[244:247], v[6:9]
	v_mfma_f32_16x16x32_bf16 v[2:5], v[178:181], v[244:247], v[2:5]
	s_setprio 2
	s_barrier
	s_add_i32 s23, s23, 2
	s_add_u32 s2, s2, 0x100
	s_addc_u32 s3, s3, 0
	s_add_u32 s18, s18, 0x100
	s_addc_u32 s19, s19, 0
	s_cmp_gt_u32 s23, 29
	s_cbranch_scc0 .LBB0_387
	s_and_b64 vcc, exec, s[30:31]
	s_cbranch_vccz .LBB0_390
	s_barrier

.LBB0_1966:
	ds_read_b128 v[130:133], v169
	ds_read_b128 v[134:137], v169 offset:1024
	ds_read_b128 v[154:157], v169 offset:2048
	ds_read_b128 v[158:161], v169 offset:3072
	ds_read_b128 v[172:175], v170
	ds_read_b128 v[176:179], v170 offset:1024
	ds_read_b128 v[180:183], v170 offset:2048
	ds_read_b128 v[184:187], v170 offset:3072
	s_add_u32 s30, s28, 0xfff80080
	s_addc_u32 s31, s29, -1
	s_cmp_eq_u32 s51, 28
	s_cselect_b32 s35, s19, s31
	s_cselect_b32 s34, s25, s30
	s_cselect_b32 s31, s17, s50
	s_cselect_b32 s30, s27, s49
	v_lshl_add_u64 v[200:201], s[28:29], 0, v[146:147]
	s_add_i32 m0, s36, 0xc000
	ds_read_b128 v[188:191], v171
	ds_read_b128 v[192:195], v171 offset:1024
	ds_read_b128 v[196:199], v171 offset:2048
	ds_read_b128 v[204:207], v171 offset:3072
	ds_read_b128 v[208:211], v171 offset:4096
	ds_read_b128 v[212:215], v171 offset:5120
	ds_read_b128 v[216:219], v171 offset:6144
	ds_read_b128 v[220:223], v171 offset:7168
	global_load_lds_dwordx4 v[200:201], off
	v_lshl_add_u64 v[200:201], s[28:29], 0, v[148:149]
	s_add_i32 m0, s36, 0xe000
	s_nop 0
	global_load_lds_dwordx4 v[200:201], off
	s_waitcnt vmcnt(8)
	s_waitcnt lgkmcnt(0)
	s_barrier
	s_setprio 1
	s_waitcnt lgkmcnt(0)
	v_mfma_f32_16x16x32_bf16 v[126:129], v[130:133], v[188:191], v[126:129]
	v_mfma_f32_16x16x32_bf16 v[122:125], v[154:157], v[188:191], v[122:125]
	v_mfma_f32_16x16x32_bf16 v[110:113], v[130:133], v[196:199], v[110:113]
	v_mfma_f32_16x16x32_bf16 v[106:109], v[154:157], v[196:199], v[106:109]
	v_mfma_f32_16x16x32_bf16 v[94:97], v[130:133], v[208:211], v[94:97]
	v_mfma_f32_16x16x32_bf16 v[90:93], v[154:157], v[208:211], v[90:93]
	v_mfma_f32_16x16x32_bf16 v[78:81], v[130:133], v[216:219], v[78:81]
	v_mfma_f32_16x16x32_bf16 v[74:77], v[154:157], v[216:219], v[74:77]
	v_mfma_f32_16x16x32_bf16 v[126:129], v[134:137], v[192:195], v[126:129]
	v_mfma_f32_16x16x32_bf16 v[122:125], v[158:161], v[192:195], v[122:125]
	v_mfma_f32_16x16x32_bf16 v[110:113], v[134:137], v[204:207], v[110:113]
	v_mfma_f32_16x16x32_bf16 v[106:109], v[158:161], v[204:207], v[106:109]
	v_mfma_f32_16x16x32_bf16 v[94:97], v[134:137], v[212:215], v[94:97]
	v_mfma_f32_16x16x32_bf16 v[90:93], v[158:161], v[212:215], v[90:93]
	v_mfma_f32_16x16x32_bf16 v[78:81], v[134:137], v[220:223], v[78:81]
	v_mfma_f32_16x16x32_bf16 v[74:77], v[158:161], v[220:223], v[74:77]
	s_setprio 0
	s_setprio 1
	v_mfma_f32_16x16x32_bf16 v[118:121], v[172:175], v[188:191], v[118:121]
	v_mfma_f32_16x16x32_bf16 v[114:117], v[180:183], v[188:191], v[114:117]
	v_mfma_f32_16x16x32_bf16 v[102:105], v[172:175], v[196:199], v[102:105]
	v_mfma_f32_16x16x32_bf16 v[98:101], v[180:183], v[196:199], v[98:101]
	v_mfma_f32_16x16x32_bf16 v[86:89], v[172:175], v[208:211], v[86:89]
	v_mfma_f32_16x16x32_bf16 v[82:85], v[180:183], v[208:211], v[82:85]
	v_mfma_f32_16x16x32_bf16 v[70:73], v[172:175], v[216:219], v[70:73]
	v_mfma_f32_16x16x32_bf16 v[66:69], v[180:183], v[216:219], v[66:69]
	v_mfma_f32_16x16x32_bf16 v[118:121], v[176:179], v[192:195], v[118:121]
	v_mfma_f32_16x16x32_bf16 v[114:117], v[184:187], v[192:195], v[114:117]
	v_mfma_f32_16x16x32_bf16 v[102:105], v[176:179], v[204:207], v[102:105]
	v_mfma_f32_16x16x32_bf16 v[98:101], v[184:187], v[204:207], v[98:101]
	v_mfma_f32_16x16x32_bf16 v[86:89], v[176:179], v[212:215], v[86:89]
	v_mfma_f32_16x16x32_bf16 v[82:85], v[184:187], v[212:215], v[82:85]
	v_mfma_f32_16x16x32_bf16 v[70:73], v[176:179], v[220:223], v[70:73]
	v_mfma_f32_16x16x32_bf16 v[66:69], v[184:187], v[220:223], v[66:69]
	s_setprio 2
	s_barrier
	s_add_i32 s52, s45, s13
	v_lshl_add_u64 v[200:201], s[30:31], 0, v[138:139]
	s_mov_b32 m0, s52
	ds_read_b128 v[188:191], v171 offset:16384
	ds_read_b128 v[192:195], v171 offset:17408
	ds_read_b128 v[196:199], v171 offset:18432
	ds_read_b128 v[204:207], v171 offset:19456
	ds_read_b128 v[208:211], v171 offset:20480
	ds_read_b128 v[212:215], v171 offset:21504
	ds_read_b128 v[216:219], v171 offset:22528
	ds_read_b128 v[220:223], v171 offset:23552
	global_load_lds_dwordx4 v[200:201], off
	s_add_i32 m0, s52, 0x2000
	s_add_u32 s52, s30, 0x80000
	v_lshl_add_u64 v[224:225], s[30:31], 0, v[140:141]
	s_addc_u32 s53, s31, 0
	s_add_i32 s54, s46, s13
	global_load_lds_dwordx4 v[224:225], off
	v_lshl_add_u64 v[226:227], s[52:53], 0, v[138:139]
	s_mov_b32 m0, s54
	v_lshl_add_u64 v[228:229], s[34:35], 0, v[140:141]
	global_load_lds_dwordx4 v[226:227], off
	v_lshl_add_u64 v[226:227], s[52:53], 0, v[140:141]
	s_add_i32 m0, s54, 0x2000
	s_nop 0
	global_load_lds_dwordx4 v[226:227], off
	v_lshl_add_u64 v[226:227], s[34:35], 0, v[138:139]
	s_mov_b32 m0, s36
	s_nop 0
	global_load_lds_dwordx4 v[226:227], off
	s_mov_b32 m0, s37
	s_nop 0
	global_load_lds_dwordx4 v[228:229], off
	s_waitcnt vmcnt(8)
	s_waitcnt lgkmcnt(0)
	s_barrier
	s_setprio 1
	s_waitcnt lgkmcnt(0)
	v_mfma_f32_16x16x32_bf16 v[62:65], v[130:133], v[188:191], v[62:65]
	v_mfma_f32_16x16x32_bf16 v[58:61], v[154:157], v[188:191], v[58:61]
	v_mfma_f32_16x16x32_bf16 v[46:49], v[130:133], v[196:199], v[46:49]
	v_mfma_f32_16x16x32_bf16 v[42:45], v[154:157], v[196:199], v[42:45]
	v_mfma_f32_16x16x32_bf16 v[30:33], v[130:133], v[208:211], v[30:33]
	v_mfma_f32_16x16x32_bf16 v[26:29], v[154:157], v[208:211], v[26:29]
	v_mfma_f32_16x16x32_bf16 v[14:17], v[130:133], v[216:219], v[14:17]
	v_mfma_f32_16x16x32_bf16 v[10:13], v[154:157], v[216:219], v[10:13]
	v_mfma_f32_16x16x32_bf16 v[62:65], v[134:137], v[192:195], v[62:65]
	v_mfma_f32_16x16x32_bf16 v[58:61], v[158:161], v[192:195], v[58:61]
	v_mfma_f32_16x16x32_bf16 v[46:49], v[134:137], v[204:207], v[46:49]
	v_mfma_f32_16x16x32_bf16 v[42:45], v[158:161], v[204:207], v[42:45]
	v_mfma_f32_16x16x32_bf16 v[30:33], v[134:137], v[212:215], v[30:33]
	v_mfma_f32_16x16x32_bf16 v[26:29], v[158:161], v[212:215], v[26:29]
	v_mfma_f32_16x16x32_bf16 v[14:17], v[134:137], v[220:223], v[14:17]
	v_mfma_f32_16x16x32_bf16 v[10:13], v[158:161], v[220:223], v[10:13]
	s_setprio 0
	s_setprio 1
	v_mfma_f32_16x16x32_bf16 v[54:57], v[172:175], v[188:191], v[54:57]
	v_mfma_f32_16x16x32_bf16 v[50:53], v[180:183], v[188:191], v[50:53]
	v_mfma_f32_16x16x32_bf16 v[38:41], v[172:175], v[196:199], v[38:41]
	v_mfma_f32_16x16x32_bf16 v[34:37], v[180:183], v[196:199], v[34:37]
	v_mfma_f32_16x16x32_bf16 v[22:25], v[172:175], v[208:211], v[22:25]
	v_mfma_f32_16x16x32_bf16 v[18:21], v[180:183], v[208:211], v[18:21]
	v_mfma_f32_16x16x32_bf16 v[6:9], v[172:175], v[216:219], v[6:9]
	v_mfma_f32_16x16x32_bf16 v[2:5], v[180:183], v[216:219], v[2:5]
	v_mfma_f32_16x16x32_bf16 v[54:57], v[176:179], v[192:195], v[54:57]
	v_mfma_f32_16x16x32_bf16 v[50:53], v[184:187], v[192:195], v[50:53]
	v_mfma_f32_16x16x32_bf16 v[38:41], v[176:179], v[204:207], v[38:41]
	v_mfma_f32_16x16x32_bf16 v[34:37], v[184:187], v[204:207], v[34:37]
	v_mfma_f32_16x16x32_bf16 v[22:25], v[176:179], v[212:215], v[22:25]
	v_mfma_f32_16x16x32_bf16 v[18:21], v[184:187], v[212:215], v[18:21]
	v_mfma_f32_16x16x32_bf16 v[6:9], v[176:179], v[220:223], v[6:9]
	v_mfma_f32_16x16x32_bf16 v[2:5], v[184:187], v[220:223], v[2:5]
	s_setprio 2
	s_barrier
	s_add_i32 s52, 0, 0x18000
	s_add_i32 s53, 0, 0x1c000
	v_add_u32_e32 v158, s52, v163
	v_add_u32_e32 v184, s53, v163
	ds_read_b128 v[130:133], v158
	ds_read_b128 v[134:137], v158 offset:1024
	ds_read_b128 v[154:157], v158 offset:2048
	ds_read_b128 v[158:161], v158 offset:3072
	ds_read_b128 v[172:175], v184
	ds_read_b128 v[176:179], v184 offset:1024
	ds_read_b128 v[180:183], v184 offset:2048
	ds_read_b128 v[184:187], v184 offset:3072
	s_add_u32 s34, s34, 0x80000
	s_addc_u32 s35, s35, 0
	s_mov_b32 m0, s38
	v_lshl_add_u64 v[230:231], s[34:35], 0, v[138:139]
	ds_read_b128 v[188:191], v171 offset:32768
	ds_read_b128 v[192:195], v171 offset:33792
	ds_read_b128 v[196:199], v171 offset:34816
	ds_read_b128 v[204:207], v171 offset:35840
	ds_read_b128 v[208:211], v171 offset:36864
	ds_read_b128 v[212:215], v171 offset:37888
	ds_read_b128 v[216:219], v171 offset:38912
	ds_read_b128 v[220:223], v171 offset:39936
	global_load_lds_dwordx4 v[230:231], off
	v_lshl_add_u64 v[230:231], s[34:35], 0, v[140:141]
	s_mov_b32 m0, s39
	s_nop 0
	global_load_lds_dwordx4 v[230:231], off
	s_waitcnt vmcnt(8)
	s_waitcnt lgkmcnt(0)
	s_barrier
	s_setprio 1
	s_waitcnt lgkmcnt(0)
	v_mfma_f32_16x16x32_bf16 v[126:129], v[130:133], v[188:191], v[126:129]
	v_mfma_f32_16x16x32_bf16 v[122:125], v[154:157], v[188:191], v[122:125]
	v_mfma_f32_16x16x32_bf16 v[110:113], v[130:133], v[196:199], v[110:113]
	v_mfma_f32_16x16x32_bf16 v[106:109], v[154:157], v[196:199], v[106:109]
	v_mfma_f32_16x16x32_bf16 v[94:97], v[130:133], v[208:211], v[94:97]
	v_mfma_f32_16x16x32_bf16 v[90:93], v[154:157], v[208:211], v[90:93]
	v_mfma_f32_16x16x32_bf16 v[78:81], v[130:133], v[216:219], v[78:81]
	v_mfma_f32_16x16x32_bf16 v[74:77], v[154:157], v[216:219], v[74:77]
	v_mfma_f32_16x16x32_bf16 v[126:129], v[134:137], v[192:195], v[126:129]
	v_mfma_f32_16x16x32_bf16 v[122:125], v[158:161], v[192:195], v[122:125]
	v_mfma_f32_16x16x32_bf16 v[110:113], v[134:137], v[204:207], v[110:113]
	v_mfma_f32_16x16x32_bf16 v[106:109], v[158:161], v[204:207], v[106:109]
	v_mfma_f32_16x16x32_bf16 v[94:97], v[134:137], v[212:215], v[94:97]
	v_mfma_f32_16x16x32_bf16 v[90:93], v[158:161], v[212:215], v[90:93]
	v_mfma_f32_16x16x32_bf16 v[78:81], v[134:137], v[220:223], v[78:81]
	v_mfma_f32_16x16x32_bf16 v[74:77], v[158:161], v[220:223], v[74:77]
	s_setprio 0
	s_setprio 1
	v_mfma_f32_16x16x32_bf16 v[118:121], v[172:175], v[188:191], v[118:121]
	v_mfma_f32_16x16x32_bf16 v[114:117], v[180:183], v[188:191], v[114:117]
	v_mfma_f32_16x16x32_bf16 v[102:105], v[172:175], v[196:199], v[102:105]
	v_mfma_f32_16x16x32_bf16 v[98:101], v[180:183], v[196:199], v[98:101]
	v_mfma_f32_16x16x32_bf16 v[86:89], v[172:175], v[208:211], v[86:89]
	v_mfma_f32_16x16x32_bf16 v[82:85], v[180:183], v[208:211], v[82:85]
	v_mfma_f32_16x16x32_bf16 v[70:73], v[172:175], v[216:219], v[70:73]
	v_mfma_f32_16x16x32_bf16 v[66:69], v[180:183], v[216:219], v[66:69]
	v_mfma_f32_16x16x32_bf16 v[118:121], v[176:179], v[192:195], v[118:121]
	v_mfma_f32_16x16x32_bf16 v[114:117], v[184:187], v[192:195], v[114:117]
	v_mfma_f32_16x16x32_bf16 v[102:105], v[176:179], v[204:207], v[102:105]
	v_mfma_f32_16x16x32_bf16 v[98:101], v[184:187], v[204:207], v[98:101]
	v_mfma_f32_16x16x32_bf16 v[86:89], v[176:179], v[212:215], v[86:89]
	v_mfma_f32_16x16x32_bf16 v[82:85], v[184:187], v[212:215], v[82:85]
	v_mfma_f32_16x16x32_bf16 v[70:73], v[176:179], v[220:223], v[70:73]
	v_mfma_f32_16x16x32_bf16 v[66:69], v[184:187], v[220:223], v[66:69]
	s_setprio 2
	s_barrier
	s_add_i32 s34, s52, s13
	v_lshl_add_u64 v[200:201], v[200:201], 0, s[6:7]
	s_mov_b32 m0, s34
	ds_read_b128 v[188:191], v171 offset:49152
	ds_read_b128 v[192:195], v171 offset:50176
	ds_read_b128 v[196:199], v171 offset:51200
	ds_read_b128 v[204:207], v171 offset:52224
	ds_read_b128 v[208:211], v171 offset:53248
	ds_read_b128 v[212:215], v171 offset:54272
	ds_read_b128 v[216:219], v171 offset:55296
	ds_read_b128 v[220:223], v171 offset:56320
	global_load_lds_dwordx4 v[200:201], off
	s_add_i32 m0, s34, 0x2000
	s_add_u32 s30, s30, 0x80080
	v_lshl_add_u64 v[200:201], v[224:225], 0, s[6:7]
	s_addc_u32 s31, s31, 0
	s_add_i32 s34, s53, s13
	global_load_lds_dwordx4 v[200:201], off
	v_lshl_add_u64 v[200:201], s[30:31], 0, v[138:139]
	s_mov_b32 m0, s34
	s_nop 0
	global_load_lds_dwordx4 v[200:201], off
	v_lshl_add_u64 v[200:201], s[30:31], 0, v[140:141]
	s_add_i32 m0, s34, 0x2000
	s_nop 0
	global_load_lds_dwordx4 v[200:201], off
	v_lshl_add_u64 v[200:201], v[226:227], 0, s[6:7]
	s_mov_b32 m0, s40
	s_nop 0
	global_load_lds_dwordx4 v[200:201], off
	v_lshl_add_u64 v[200:201], v[228:229], 0, s[6:7]
	s_mov_b32 m0, s41
	s_nop 0
	global_load_lds_dwordx4 v[200:201], off
	s_waitcnt vmcnt(8)
	s_waitcnt lgkmcnt(0)
	s_barrier
	s_setprio 1
	s_waitcnt lgkmcnt(0)
	v_mfma_f32_16x16x32_bf16 v[62:65], v[130:133], v[188:191], v[62:65]
	v_mfma_f32_16x16x32_bf16 v[58:61], v[154:157], v[188:191], v[58:61]
	v_mfma_f32_16x16x32_bf16 v[46:49], v[130:133], v[196:199], v[46:49]
	v_mfma_f32_16x16x32_bf16 v[42:45], v[154:157], v[196:199], v[42:45]
	v_mfma_f32_16x16x32_bf16 v[30:33], v[130:133], v[208:211], v[30:33]
	v_mfma_f32_16x16x32_bf16 v[26:29], v[154:157], v[208:211], v[26:29]
	v_mfma_f32_16x16x32_bf16 v[14:17], v[130:133], v[216:219], v[14:17]
	v_mfma_f32_16x16x32_bf16 v[10:13], v[154:157], v[216:219], v[10:13]
	v_mfma_f32_16x16x32_bf16 v[62:65], v[134:137], v[192:195], v[62:65]
	v_mfma_f32_16x16x32_bf16 v[58:61], v[158:161], v[192:195], v[58:61]
	v_mfma_f32_16x16x32_bf16 v[46:49], v[134:137], v[204:207], v[46:49]
	v_mfma_f32_16x16x32_bf16 v[42:45], v[158:161], v[204:207], v[42:45]
	v_mfma_f32_16x16x32_bf16 v[30:33], v[134:137], v[212:215], v[30:33]
	v_mfma_f32_16x16x32_bf16 v[26:29], v[158:161], v[212:215], v[26:29]
	v_mfma_f32_16x16x32_bf16 v[14:17], v[134:137], v[220:223], v[14:17]
	v_mfma_f32_16x16x32_bf16 v[10:13], v[158:161], v[220:223], v[10:13]
	s_setprio 0
	s_setprio 1
	v_mfma_f32_16x16x32_bf16 v[54:57], v[172:175], v[188:191], v[54:57]
	v_mfma_f32_16x16x32_bf16 v[50:53], v[180:183], v[188:191], v[50:53]
	v_mfma_f32_16x16x32_bf16 v[38:41], v[172:175], v[196:199], v[38:41]
	v_mfma_f32_16x16x32_bf16 v[34:37], v[180:183], v[196:199], v[34:37]
	v_mfma_f32_16x16x32_bf16 v[22:25], v[172:175], v[208:211], v[22:25]
	v_mfma_f32_16x16x32_bf16 v[18:21], v[180:183], v[208:211], v[18:21]
	v_mfma_f32_16x16x32_bf16 v[6:9], v[172:175], v[216:219], v[6:9]
	v_mfma_f32_16x16x32_bf16 v[2:5], v[180:183], v[216:219], v[2:5]
	v_mfma_f32_16x16x32_bf16 v[54:57], v[176:179], v[192:195], v[54:57]
	v_mfma_f32_16x16x32_bf16 v[50:53], v[184:187], v[192:195], v[50:53]
	v_mfma_f32_16x16x32_bf16 v[38:41], v[176:179], v[204:207], v[38:41]
	v_mfma_f32_16x16x32_bf16 v[34:37], v[184:187], v[204:207], v[34:37]
	v_mfma_f32_16x16x32_bf16 v[22:25], v[176:179], v[212:215], v[22:25]
	v_mfma_f32_16x16x32_bf16 v[18:21], v[184:187], v[212:215], v[18:21]
	v_mfma_f32_16x16x32_bf16 v[6:9], v[176:179], v[220:223], v[6:9]
	v_mfma_f32_16x16x32_bf16 v[2:5], v[184:187], v[220:223], v[2:5]
	s_setprio 2
	s_barrier
	s_add_i32 s51, s51, 2
	s_add_u32 s28, s28, 0x100
	s_addc_u32 s29, s29, 0
	s_add_u32 s49, s49, 0x100
	s_addc_u32 s50, s50, 0
	s_cmp_gt_u32 s51, 29
	s_cbranch_scc0 .LBB0_1966
	s_and_b64 vcc, exec, s[8:9]
	s_cbranch_vccz .LBB0_1969
	s_barrier

.LBB0_2068:
	ds_read_b128 v[106:109], v199
	ds_read_b128 v[114:117], v199 offset:1024
	ds_read_b128 v[118:121], v199 offset:2048
	ds_read_b128 v[122:125], v199 offset:3072
	ds_read_b128 v[126:129], v200
	ds_read_b128 v[134:137], v200 offset:1024
	ds_read_b128 v[138:141], v200 offset:2048
	ds_read_b128 v[142:145], v200 offset:3072
	s_add_u32 s26, s24, 0xfff80080
	s_addc_u32 s27, s25, -1
	s_cmp_eq_u32 s49, 28
	s_cselect_b32 s29, s15, s27
	s_cselect_b32 s28, s21, s26
	s_cselect_b32 s27, s13, s48
	s_cselect_b32 s26, s23, s47
	v_lshl_add_u64 v[224:225], s[24:25], 0, v[186:187]
	s_add_i32 m0, s31, 0xc000
	ds_read_b128 v[146:149], v201
	ds_read_b128 v[166:169], v201 offset:1024
	ds_read_b128 v[170:173], v201 offset:2048
	ds_read_b128 v[204:207], v201 offset:3072
	ds_read_b128 v[208:211], v201 offset:4096
	ds_read_b128 v[212:215], v201 offset:5120
	ds_read_b128 v[216:219], v201 offset:6144
	ds_read_b128 v[220:223], v201 offset:7168
	global_load_lds_dwordx4 v[224:225], off
	v_lshl_add_u64 v[224:225], s[24:25], 0, v[188:189]
	s_add_i32 m0, s31, 0xe000
	s_nop 0
	global_load_lds_dwordx4 v[224:225], off
	s_waitcnt vmcnt(8)
	s_waitcnt lgkmcnt(0)
	s_barrier
	s_setprio 1
	s_waitcnt lgkmcnt(0)
	v_mfma_f32_16x16x32_bf16 v[162:165], v[106:109], v[146:149], v[162:165]
	v_mfma_f32_16x16x32_bf16 v[158:161], v[118:121], v[146:149], v[158:161]
	v_mfma_f32_16x16x32_bf16 v[130:133], v[106:109], v[170:173], v[130:133]
	v_mfma_f32_16x16x32_bf16 v[110:113], v[118:121], v[170:173], v[110:113]
	v_mfma_f32_16x16x32_bf16 v[94:97], v[106:109], v[208:211], v[94:97]
	v_mfma_f32_16x16x32_bf16 v[90:93], v[118:121], v[208:211], v[90:93]
	v_mfma_f32_16x16x32_bf16 v[78:81], v[106:109], v[216:219], v[78:81]
	v_mfma_f32_16x16x32_bf16 v[74:77], v[118:121], v[216:219], v[74:77]
	v_mfma_f32_16x16x32_bf16 v[162:165], v[114:117], v[166:169], v[162:165]
	v_mfma_f32_16x16x32_bf16 v[158:161], v[122:125], v[166:169], v[158:161]
	v_mfma_f32_16x16x32_bf16 v[130:133], v[114:117], v[204:207], v[130:133]
	v_mfma_f32_16x16x32_bf16 v[110:113], v[122:125], v[204:207], v[110:113]
	v_mfma_f32_16x16x32_bf16 v[94:97], v[114:117], v[212:215], v[94:97]
	v_mfma_f32_16x16x32_bf16 v[90:93], v[122:125], v[212:215], v[90:93]
	v_mfma_f32_16x16x32_bf16 v[78:81], v[114:117], v[220:223], v[78:81]
	v_mfma_f32_16x16x32_bf16 v[74:77], v[122:125], v[220:223], v[74:77]
	s_setprio 0
	s_setprio 1
	v_mfma_f32_16x16x32_bf16 v[154:157], v[126:129], v[146:149], v[154:157]
	v_mfma_f32_16x16x32_bf16 v[102:105], v[126:129], v[170:173], v[102:105]
	v_mfma_f32_16x16x32_bf16 v[98:101], v[138:141], v[170:173], v[98:101]
	v_mfma_f32_16x16x32_bf16 v[86:89], v[126:129], v[208:211], v[86:89]
	v_mfma_f32_16x16x32_bf16 v[82:85], v[138:141], v[208:211], v[82:85]
	v_mfma_f32_16x16x32_bf16 v[70:73], v[126:129], v[216:219], v[70:73]
	v_mfma_f32_16x16x32_bf16 v[66:69], v[138:141], v[216:219], v[66:69]
	v_mfma_f32_16x16x32_bf16 v[154:157], v[134:137], v[166:169], v[154:157]
	v_mfma_f32_16x16x32_bf16 v[146:149], v[138:141], v[146:149], v[150:153]
	v_mfma_f32_16x16x32_bf16 v[102:105], v[134:137], v[204:207], v[102:105]
	v_mfma_f32_16x16x32_bf16 v[98:101], v[142:145], v[204:207], v[98:101]
	v_mfma_f32_16x16x32_bf16 v[86:89], v[134:137], v[212:215], v[86:89]
	v_mfma_f32_16x16x32_bf16 v[82:85], v[142:145], v[212:215], v[82:85]
	v_mfma_f32_16x16x32_bf16 v[70:73], v[134:137], v[220:223], v[70:73]
	v_mfma_f32_16x16x32_bf16 v[66:69], v[142:145], v[220:223], v[66:69]
	v_mfma_f32_16x16x32_bf16 v[146:149], v[142:145], v[166:169], v[146:149]
	s_setprio 2
	s_barrier
	s_add_i32 s50, s42, s30
	v_lshl_add_u64 v[224:225], s[26:27], 0, v[176:177]
	s_mov_b32 m0, s50
	ds_read_b128 v[150:153], v201 offset:16384
	ds_read_b128 v[166:169], v201 offset:17408
	ds_read_b128 v[170:173], v201 offset:18432
	ds_read_b128 v[204:207], v201 offset:19456
	ds_read_b128 v[208:211], v201 offset:20480
	ds_read_b128 v[212:215], v201 offset:21504
	ds_read_b128 v[216:219], v201 offset:22528
	ds_read_b128 v[220:223], v201 offset:23552
	global_load_lds_dwordx4 v[224:225], off
	s_add_i32 m0, s50, 0x2000
	s_add_u32 s50, s26, 0x80000
	v_lshl_add_u64 v[226:227], s[26:27], 0, v[180:181]
	s_addc_u32 s51, s27, 0
	s_add_i32 s52, s43, s30
	global_load_lds_dwordx4 v[226:227], off
	v_lshl_add_u64 v[228:229], s[50:51], 0, v[176:177]
	s_mov_b32 m0, s52
	v_lshl_add_u64 v[230:231], s[28:29], 0, v[178:179]
	global_load_lds_dwordx4 v[228:229], off
	v_lshl_add_u64 v[228:229], s[50:51], 0, v[180:181]
	s_add_i32 m0, s52, 0x2000
	s_nop 0
	global_load_lds_dwordx4 v[228:229], off
	v_lshl_add_u64 v[228:229], s[28:29], 0, v[174:175]
	s_mov_b32 m0, s31
	s_nop 0
	global_load_lds_dwordx4 v[228:229], off
	s_mov_b32 m0, s34
	s_nop 0
	global_load_lds_dwordx4 v[230:231], off
	s_waitcnt vmcnt(8)
	s_waitcnt lgkmcnt(0)
	s_barrier
	s_setprio 1
	s_waitcnt lgkmcnt(0)
	v_mfma_f32_16x16x32_bf16 v[62:65], v[106:109], v[150:153], v[62:65]
	v_mfma_f32_16x16x32_bf16 v[58:61], v[118:121], v[150:153], v[58:61]
	v_mfma_f32_16x16x32_bf16 v[46:49], v[106:109], v[170:173], v[46:49]
	v_mfma_f32_16x16x32_bf16 v[42:45], v[118:121], v[170:173], v[42:45]
	v_mfma_f32_16x16x32_bf16 v[30:33], v[106:109], v[208:211], v[30:33]
	v_mfma_f32_16x16x32_bf16 v[26:29], v[118:121], v[208:211], v[26:29]
	v_mfma_f32_16x16x32_bf16 v[14:17], v[106:109], v[216:219], v[14:17]
	v_mfma_f32_16x16x32_bf16 v[10:13], v[118:121], v[216:219], v[10:13]
	v_mfma_f32_16x16x32_bf16 v[62:65], v[114:117], v[166:169], v[62:65]
	v_mfma_f32_16x16x32_bf16 v[58:61], v[122:125], v[166:169], v[58:61]
	v_mfma_f32_16x16x32_bf16 v[46:49], v[114:117], v[204:207], v[46:49]
	v_mfma_f32_16x16x32_bf16 v[42:45], v[122:125], v[204:207], v[42:45]
	v_mfma_f32_16x16x32_bf16 v[30:33], v[114:117], v[212:215], v[30:33]
	v_mfma_f32_16x16x32_bf16 v[26:29], v[122:125], v[212:215], v[26:29]
	v_mfma_f32_16x16x32_bf16 v[14:17], v[114:117], v[220:223], v[14:17]
	v_mfma_f32_16x16x32_bf16 v[10:13], v[122:125], v[220:223], v[10:13]
	s_setprio 0
	s_setprio 1
	v_mfma_f32_16x16x32_bf16 v[54:57], v[126:129], v[150:153], v[54:57]
	v_mfma_f32_16x16x32_bf16 v[50:53], v[138:141], v[150:153], v[50:53]
	v_mfma_f32_16x16x32_bf16 v[38:41], v[126:129], v[170:173], v[38:41]
	v_mfma_f32_16x16x32_bf16 v[34:37], v[138:141], v[170:173], v[34:37]
	v_mfma_f32_16x16x32_bf16 v[22:25], v[126:129], v[208:211], v[22:25]
	v_mfma_f32_16x16x32_bf16 v[18:21], v[138:141], v[208:211], v[18:21]
	v_mfma_f32_16x16x32_bf16 v[6:9], v[126:129], v[216:219], v[6:9]
	v_mfma_f32_16x16x32_bf16 v[2:5], v[138:141], v[216:219], v[2:5]
	v_mfma_f32_16x16x32_bf16 v[54:57], v[134:137], v[166:169], v[54:57]
	v_mfma_f32_16x16x32_bf16 v[50:53], v[142:145], v[166:169], v[50:53]
	v_mfma_f32_16x16x32_bf16 v[38:41], v[134:137], v[204:207], v[38:41]
	v_mfma_f32_16x16x32_bf16 v[34:37], v[142:145], v[204:207], v[34:37]
	v_mfma_f32_16x16x32_bf16 v[22:25], v[134:137], v[212:215], v[22:25]
	v_mfma_f32_16x16x32_bf16 v[18:21], v[142:145], v[212:215], v[18:21]
	v_mfma_f32_16x16x32_bf16 v[6:9], v[134:137], v[220:223], v[6:9]
	v_mfma_f32_16x16x32_bf16 v[2:5], v[142:145], v[220:223], v[2:5]
	s_setprio 2
	s_barrier
	s_add_i32 s50, 0, 0x18000
	s_add_i32 s51, 0, 0x1c000
	v_add_u32_e32 v122, s50, v195
	v_add_u32_e32 v142, s51, v195
	ds_read_b128 v[106:109], v122
	ds_read_b128 v[114:117], v122 offset:1024
	ds_read_b128 v[118:121], v122 offset:2048
	ds_read_b128 v[122:125], v122 offset:3072
	ds_read_b128 v[126:129], v142
	ds_read_b128 v[134:137], v142 offset:1024
	ds_read_b128 v[138:141], v142 offset:2048
	ds_read_b128 v[142:145], v142 offset:3072
	s_add_u32 s28, s28, 0x80000
	s_addc_u32 s29, s29, 0
	s_mov_b32 m0, s35
	v_lshl_add_u64 v[232:233], s[28:29], 0, v[174:175]
	ds_read_b128 v[150:153], v201 offset:32768
	ds_read_b128 v[166:169], v201 offset:33792
	ds_read_b128 v[170:173], v201 offset:34816
	ds_read_b128 v[204:207], v201 offset:35840
	ds_read_b128 v[208:211], v201 offset:36864
	ds_read_b128 v[212:215], v201 offset:37888
	ds_read_b128 v[216:219], v201 offset:38912
	ds_read_b128 v[220:223], v201 offset:39936
	global_load_lds_dwordx4 v[232:233], off
	v_lshl_add_u64 v[232:233], s[28:29], 0, v[178:179]
	s_mov_b32 m0, s37
	s_nop 0
	global_load_lds_dwordx4 v[232:233], off
	s_waitcnt vmcnt(8)
	s_waitcnt lgkmcnt(0)
	s_barrier
	s_setprio 1
	s_waitcnt lgkmcnt(0)
	v_mfma_f32_16x16x32_bf16 v[162:165], v[106:109], v[150:153], v[162:165]
	v_mfma_f32_16x16x32_bf16 v[158:161], v[118:121], v[150:153], v[158:161]
	v_mfma_f32_16x16x32_bf16 v[130:133], v[106:109], v[170:173], v[130:133]
	v_mfma_f32_16x16x32_bf16 v[110:113], v[118:121], v[170:173], v[110:113]
	v_mfma_f32_16x16x32_bf16 v[94:97], v[106:109], v[208:211], v[94:97]
	v_mfma_f32_16x16x32_bf16 v[90:93], v[118:121], v[208:211], v[90:93]
	v_mfma_f32_16x16x32_bf16 v[78:81], v[106:109], v[216:219], v[78:81]
	v_mfma_f32_16x16x32_bf16 v[74:77], v[118:121], v[216:219], v[74:77]
	v_mfma_f32_16x16x32_bf16 v[162:165], v[114:117], v[166:169], v[162:165]
	v_mfma_f32_16x16x32_bf16 v[158:161], v[122:125], v[166:169], v[158:161]
	v_mfma_f32_16x16x32_bf16 v[130:133], v[114:117], v[204:207], v[130:133]
	v_mfma_f32_16x16x32_bf16 v[110:113], v[122:125], v[204:207], v[110:113]
	v_mfma_f32_16x16x32_bf16 v[94:97], v[114:117], v[212:215], v[94:97]
	v_mfma_f32_16x16x32_bf16 v[90:93], v[122:125], v[212:215], v[90:93]
	v_mfma_f32_16x16x32_bf16 v[78:81], v[114:117], v[220:223], v[78:81]
	v_mfma_f32_16x16x32_bf16 v[74:77], v[122:125], v[220:223], v[74:77]
	s_setprio 0
	s_setprio 1
	v_mfma_f32_16x16x32_bf16 v[154:157], v[126:129], v[150:153], v[154:157]
	v_mfma_f32_16x16x32_bf16 v[146:149], v[138:141], v[150:153], v[146:149]
	v_mfma_f32_16x16x32_bf16 v[102:105], v[126:129], v[170:173], v[102:105]
	v_mfma_f32_16x16x32_bf16 v[98:101], v[138:141], v[170:173], v[98:101]
	v_mfma_f32_16x16x32_bf16 v[86:89], v[126:129], v[208:211], v[86:89]
	v_mfma_f32_16x16x32_bf16 v[82:85], v[138:141], v[208:211], v[82:85]
	v_mfma_f32_16x16x32_bf16 v[70:73], v[126:129], v[216:219], v[70:73]
	v_mfma_f32_16x16x32_bf16 v[66:69], v[138:141], v[216:219], v[66:69]
	v_mfma_f32_16x16x32_bf16 v[154:157], v[134:137], v[166:169], v[154:157]
	v_mfma_f32_16x16x32_bf16 v[150:153], v[142:145], v[166:169], v[146:149]
	v_mfma_f32_16x16x32_bf16 v[102:105], v[134:137], v[204:207], v[102:105]
	v_mfma_f32_16x16x32_bf16 v[98:101], v[142:145], v[204:207], v[98:101]
	v_mfma_f32_16x16x32_bf16 v[86:89], v[134:137], v[212:215], v[86:89]
	v_mfma_f32_16x16x32_bf16 v[82:85], v[142:145], v[212:215], v[82:85]
	v_mfma_f32_16x16x32_bf16 v[70:73], v[134:137], v[220:223], v[70:73]
	v_mfma_f32_16x16x32_bf16 v[66:69], v[142:145], v[220:223], v[66:69]
	s_setprio 2
	s_barrier
	s_add_i32 s28, s50, s30
	v_lshl_add_u64 v[224:225], v[224:225], 0, s[6:7]
	s_mov_b32 m0, s28
	ds_read_b128 v[146:149], v201 offset:49152
	ds_read_b128 v[166:169], v201 offset:50176
	ds_read_b128 v[170:173], v201 offset:51200
	ds_read_b128 v[204:207], v201 offset:52224
	ds_read_b128 v[208:211], v201 offset:53248
	ds_read_b128 v[212:215], v201 offset:54272
	ds_read_b128 v[216:219], v201 offset:55296
	ds_read_b128 v[220:223], v201 offset:56320
	global_load_lds_dwordx4 v[224:225], off
	s_add_i32 m0, s28, 0x2000
	s_add_u32 s26, s26, 0x80080
	v_lshl_add_u64 v[224:225], v[226:227], 0, s[6:7]
	s_addc_u32 s27, s27, 0
	s_add_i32 s28, s51, s30
	global_load_lds_dwordx4 v[224:225], off
	v_lshl_add_u64 v[224:225], s[26:27], 0, v[176:177]
	s_mov_b32 m0, s28
	s_nop 0
	global_load_lds_dwordx4 v[224:225], off
	v_lshl_add_u64 v[224:225], s[26:27], 0, v[180:181]
	s_add_i32 m0, s28, 0x2000
	s_nop 0
	global_load_lds_dwordx4 v[224:225], off
	v_lshl_add_u64 v[224:225], v[228:229], 0, s[6:7]
	s_mov_b32 m0, s38
	s_nop 0
	global_load_lds_dwordx4 v[224:225], off
	v_lshl_add_u64 v[224:225], v[230:231], 0, s[6:7]
	s_mov_b32 m0, s39
	s_nop 0
	global_load_lds_dwordx4 v[224:225], off
	s_waitcnt vmcnt(8)
	s_waitcnt lgkmcnt(0)
	s_barrier
	s_setprio 1
	s_waitcnt lgkmcnt(0)
	v_mfma_f32_16x16x32_bf16 v[62:65], v[106:109], v[146:149], v[62:65]
	v_mfma_f32_16x16x32_bf16 v[58:61], v[118:121], v[146:149], v[58:61]
	v_mfma_f32_16x16x32_bf16 v[46:49], v[106:109], v[170:173], v[46:49]
	v_mfma_f32_16x16x32_bf16 v[42:45], v[118:121], v[170:173], v[42:45]
	v_mfma_f32_16x16x32_bf16 v[30:33], v[106:109], v[208:211], v[30:33]
	v_mfma_f32_16x16x32_bf16 v[26:29], v[118:121], v[208:211], v[26:29]
	v_mfma_f32_16x16x32_bf16 v[14:17], v[106:109], v[216:219], v[14:17]
	v_mfma_f32_16x16x32_bf16 v[10:13], v[118:121], v[216:219], v[10:13]
	v_mfma_f32_16x16x32_bf16 v[62:65], v[114:117], v[166:169], v[62:65]
	v_mfma_f32_16x16x32_bf16 v[58:61], v[122:125], v[166:169], v[58:61]
	v_mfma_f32_16x16x32_bf16 v[46:49], v[114:117], v[204:207], v[46:49]
	v_mfma_f32_16x16x32_bf16 v[42:45], v[122:125], v[204:207], v[42:45]
	v_mfma_f32_16x16x32_bf16 v[30:33], v[114:117], v[212:215], v[30:33]
	v_mfma_f32_16x16x32_bf16 v[26:29], v[122:125], v[212:215], v[26:29]
	v_mfma_f32_16x16x32_bf16 v[14:17], v[114:117], v[220:223], v[14:17]
	v_mfma_f32_16x16x32_bf16 v[10:13], v[122:125], v[220:223], v[10:13]
	s_setprio 0
	s_setprio 1
	v_mfma_f32_16x16x32_bf16 v[54:57], v[126:129], v[146:149], v[54:57]
	v_mfma_f32_16x16x32_bf16 v[50:53], v[138:141], v[146:149], v[50:53]
	v_mfma_f32_16x16x32_bf16 v[38:41], v[126:129], v[170:173], v[38:41]
	v_mfma_f32_16x16x32_bf16 v[34:37], v[138:141], v[170:173], v[34:37]
	v_mfma_f32_16x16x32_bf16 v[22:25], v[126:129], v[208:211], v[22:25]
	v_mfma_f32_16x16x32_bf16 v[18:21], v[138:141], v[208:211], v[18:21]
	v_mfma_f32_16x16x32_bf16 v[6:9], v[126:129], v[216:219], v[6:9]
	v_mfma_f32_16x16x32_bf16 v[2:5], v[138:141], v[216:219], v[2:5]
	v_mfma_f32_16x16x32_bf16 v[54:57], v[134:137], v[166:169], v[54:57]
	v_mfma_f32_16x16x32_bf16 v[50:53], v[142:145], v[166:169], v[50:53]
	v_mfma_f32_16x16x32_bf16 v[38:41], v[134:137], v[204:207], v[38:41]
	v_mfma_f32_16x16x32_bf16 v[34:37], v[142:145], v[204:207], v[34:37]
	v_mfma_f32_16x16x32_bf16 v[22:25], v[134:137], v[212:215], v[22:25]
	v_mfma_f32_16x16x32_bf16 v[18:21], v[142:145], v[212:215], v[18:21]
	v_mfma_f32_16x16x32_bf16 v[6:9], v[134:137], v[220:223], v[6:9]
	v_mfma_f32_16x16x32_bf16 v[2:5], v[142:145], v[220:223], v[2:5]
	s_setprio 2
	s_barrier
	s_add_i32 s49, s49, 2
	s_add_u32 s24, s24, 0x100
	s_addc_u32 s25, s25, 0
	s_add_u32 s47, s47, 0x100
	s_addc_u32 s48, s48, 0
	s_cmp_gt_u32 s49, 29
	s_cbranch_scc0 .LBB0_2068
	s_and_b64 vcc, exec, s[8:9]
	s_cbranch_vccz .LBB0_2071
	s_barrier

.LBB0_2149:
	ds_read_b128 v[146:149], v163
	ds_read_b128 v[150:153], v163 offset:1024
	ds_read_b128 v[154:157], v163 offset:2048
	ds_read_b128 v[166:169], v163 offset:3072
	ds_read_b128 v[170:173], v164
	ds_read_b128 v[174:177], v164 offset:1024
	ds_read_b128 v[178:181], v164 offset:2048
	ds_read_b128 v[182:185], v164 offset:3072
	s_add_u32 s28, s26, 0x100
	s_addc_u32 s29, s27, 0
	s_cmpk_eq_i32 s50, 0x54
	s_cselect_b32 s35, s3, s29
	s_cselect_b32 s34, s2, s28
	s_cselect_b32 s31, s21, s25
	s_cselect_b32 s30, s20, s23
	v_lshl_add_u64 v[220:221], s[26:27], 0, v[138:139]
	s_add_i32 m0, s37, 0xc000
	ds_read_b128 v[186:189], v165
	ds_read_b128 v[190:193], v165 offset:1024
	ds_read_b128 v[194:197], v165 offset:2048
	ds_read_b128 v[198:201], v165 offset:3072
	ds_read_b128 v[204:207], v165 offset:4096
	ds_read_b128 v[208:211], v165 offset:5120
	ds_read_b128 v[212:215], v165 offset:6144
	ds_read_b128 v[216:219], v165 offset:7168
	global_load_lds_dwordx4 v[220:221], off
	v_lshl_add_u64 v[220:221], s[26:27], 0, v[140:141]
	s_add_i32 m0, s37, 0xe000
	s_nop 0
	global_load_lds_dwordx4 v[220:221], off
	s_waitcnt vmcnt(8)
	s_waitcnt lgkmcnt(0)
	s_barrier
	s_setprio 1
	s_waitcnt lgkmcnt(0)
	v_mfma_f32_16x16x32_bf16 v[126:129], v[146:149], v[186:189], v[126:129]
	v_mfma_f32_16x16x32_bf16 v[122:125], v[154:157], v[186:189], v[122:125]
	v_mfma_f32_16x16x32_bf16 v[110:113], v[146:149], v[194:197], v[110:113]
	v_mfma_f32_16x16x32_bf16 v[106:109], v[154:157], v[194:197], v[106:109]
	v_mfma_f32_16x16x32_bf16 v[94:97], v[146:149], v[204:207], v[94:97]
	v_mfma_f32_16x16x32_bf16 v[90:93], v[154:157], v[204:207], v[90:93]
	v_mfma_f32_16x16x32_bf16 v[78:81], v[146:149], v[212:215], v[78:81]
	v_mfma_f32_16x16x32_bf16 v[74:77], v[154:157], v[212:215], v[74:77]
	v_mfma_f32_16x16x32_bf16 v[126:129], v[150:153], v[190:193], v[126:129]
	v_mfma_f32_16x16x32_bf16 v[122:125], v[166:169], v[190:193], v[122:125]
	v_mfma_f32_16x16x32_bf16 v[110:113], v[150:153], v[198:201], v[110:113]
	v_mfma_f32_16x16x32_bf16 v[106:109], v[166:169], v[198:201], v[106:109]
	v_mfma_f32_16x16x32_bf16 v[94:97], v[150:153], v[208:211], v[94:97]
	v_mfma_f32_16x16x32_bf16 v[90:93], v[166:169], v[208:211], v[90:93]
	v_mfma_f32_16x16x32_bf16 v[78:81], v[150:153], v[216:219], v[78:81]
	v_mfma_f32_16x16x32_bf16 v[74:77], v[166:169], v[216:219], v[74:77]
	s_setprio 0
	s_setprio 1
	v_mfma_f32_16x16x32_bf16 v[118:121], v[170:173], v[186:189], v[118:121]
	v_mfma_f32_16x16x32_bf16 v[114:117], v[178:181], v[186:189], v[114:117]
	v_mfma_f32_16x16x32_bf16 v[102:105], v[170:173], v[194:197], v[102:105]
	v_mfma_f32_16x16x32_bf16 v[98:101], v[178:181], v[194:197], v[98:101]
	v_mfma_f32_16x16x32_bf16 v[86:89], v[170:173], v[204:207], v[86:89]
	v_mfma_f32_16x16x32_bf16 v[82:85], v[178:181], v[204:207], v[82:85]
	v_mfma_f32_16x16x32_bf16 v[70:73], v[170:173], v[212:215], v[70:73]
	v_mfma_f32_16x16x32_bf16 v[66:69], v[178:181], v[212:215], v[66:69]
	v_mfma_f32_16x16x32_bf16 v[118:121], v[174:177], v[190:193], v[118:121]
	v_mfma_f32_16x16x32_bf16 v[114:117], v[182:185], v[190:193], v[114:117]
	v_mfma_f32_16x16x32_bf16 v[102:105], v[174:177], v[198:201], v[102:105]
	v_mfma_f32_16x16x32_bf16 v[98:101], v[182:185], v[198:201], v[98:101]
	v_mfma_f32_16x16x32_bf16 v[86:89], v[174:177], v[208:211], v[86:89]
	v_mfma_f32_16x16x32_bf16 v[82:85], v[182:185], v[208:211], v[82:85]
	v_mfma_f32_16x16x32_bf16 v[70:73], v[174:177], v[216:219], v[70:73]
	v_mfma_f32_16x16x32_bf16 v[66:69], v[182:185], v[216:219], v[66:69]
	s_setprio 2
	s_barrier
	s_add_i32 s26, s44, s19
	v_lshl_add_u64 v[220:221], s[30:31], 0, v[130:131]
	s_mov_b32 m0, s26
	ds_read_b128 v[186:189], v165 offset:16384
	ds_read_b128 v[190:193], v165 offset:17408
	ds_read_b128 v[194:197], v165 offset:18432
	ds_read_b128 v[198:201], v165 offset:19456
	ds_read_b128 v[204:207], v165 offset:20480
	ds_read_b128 v[208:211], v165 offset:21504
	ds_read_b128 v[212:215], v165 offset:22528
	ds_read_b128 v[216:219], v165 offset:23552
	global_load_lds_dwordx4 v[220:221], off
	s_add_i32 m0, s26, 0x2000
	s_add_u32 s26, s30, 0x160000
	v_lshl_add_u64 v[222:223], s[30:31], 0, v[132:133]
	s_addc_u32 s27, s31, 0
	s_add_i32 s51, s45, s19
	global_load_lds_dwordx4 v[222:223], off
	v_lshl_add_u64 v[224:225], s[26:27], 0, v[130:131]
	s_mov_b32 m0, s51
	v_lshl_add_u64 v[226:227], s[34:35], 0, v[132:133]
	global_load_lds_dwordx4 v[224:225], off
	v_lshl_add_u64 v[224:225], s[26:27], 0, v[132:133]
	s_add_i32 m0, s51, 0x2000
	s_nop 0
	global_load_lds_dwordx4 v[224:225], off
	v_lshl_add_u64 v[224:225], s[34:35], 0, v[130:131]
	s_mov_b32 m0, s37
	s_nop 0
	global_load_lds_dwordx4 v[224:225], off
	s_mov_b32 m0, s38
	s_nop 0
	global_load_lds_dwordx4 v[226:227], off
	s_waitcnt vmcnt(8)
	s_waitcnt lgkmcnt(0)
	s_barrier
	s_setprio 1
	s_waitcnt lgkmcnt(0)
	v_mfma_f32_16x16x32_bf16 v[62:65], v[146:149], v[186:189], v[62:65]
	v_mfma_f32_16x16x32_bf16 v[58:61], v[154:157], v[186:189], v[58:61]
	v_mfma_f32_16x16x32_bf16 v[46:49], v[146:149], v[194:197], v[46:49]
	v_mfma_f32_16x16x32_bf16 v[42:45], v[154:157], v[194:197], v[42:45]
	v_mfma_f32_16x16x32_bf16 v[30:33], v[146:149], v[204:207], v[30:33]
	v_mfma_f32_16x16x32_bf16 v[26:29], v[154:157], v[204:207], v[26:29]
	v_mfma_f32_16x16x32_bf16 v[14:17], v[146:149], v[212:215], v[14:17]
	v_mfma_f32_16x16x32_bf16 v[10:13], v[154:157], v[212:215], v[10:13]
	v_mfma_f32_16x16x32_bf16 v[62:65], v[150:153], v[190:193], v[62:65]
	v_mfma_f32_16x16x32_bf16 v[58:61], v[166:169], v[190:193], v[58:61]
	v_mfma_f32_16x16x32_bf16 v[46:49], v[150:153], v[198:201], v[46:49]
	v_mfma_f32_16x16x32_bf16 v[42:45], v[166:169], v[198:201], v[42:45]
	v_mfma_f32_16x16x32_bf16 v[30:33], v[150:153], v[208:211], v[30:33]
	v_mfma_f32_16x16x32_bf16 v[26:29], v[166:169], v[208:211], v[26:29]
	v_mfma_f32_16x16x32_bf16 v[14:17], v[150:153], v[216:219], v[14:17]
	v_mfma_f32_16x16x32_bf16 v[10:13], v[166:169], v[216:219], v[10:13]
	s_setprio 0
	s_setprio 1
	v_mfma_f32_16x16x32_bf16 v[54:57], v[170:173], v[186:189], v[54:57]
	v_mfma_f32_16x16x32_bf16 v[50:53], v[178:181], v[186:189], v[50:53]
	v_mfma_f32_16x16x32_bf16 v[38:41], v[170:173], v[194:197], v[38:41]
	v_mfma_f32_16x16x32_bf16 v[34:37], v[178:181], v[194:197], v[34:37]
	v_mfma_f32_16x16x32_bf16 v[22:25], v[170:173], v[204:207], v[22:25]
	v_mfma_f32_16x16x32_bf16 v[18:21], v[178:181], v[204:207], v[18:21]
	v_mfma_f32_16x16x32_bf16 v[6:9], v[170:173], v[212:215], v[6:9]
	v_mfma_f32_16x16x32_bf16 v[2:5], v[178:181], v[212:215], v[2:5]
	v_mfma_f32_16x16x32_bf16 v[54:57], v[174:177], v[190:193], v[54:57]
	v_mfma_f32_16x16x32_bf16 v[50:53], v[182:185], v[190:193], v[50:53]
	v_mfma_f32_16x16x32_bf16 v[38:41], v[174:177], v[198:201], v[38:41]
	v_mfma_f32_16x16x32_bf16 v[34:37], v[182:185], v[198:201], v[34:37]
	v_mfma_f32_16x16x32_bf16 v[22:25], v[174:177], v[208:211], v[22:25]
	v_mfma_f32_16x16x32_bf16 v[18:21], v[182:185], v[208:211], v[18:21]
	v_mfma_f32_16x16x32_bf16 v[6:9], v[174:177], v[216:219], v[6:9]
	v_mfma_f32_16x16x32_bf16 v[2:5], v[182:185], v[216:219], v[2:5]
	s_setprio 2
	s_barrier
	s_add_i32 s51, 0, 0x18000
	s_add_i32 s52, 0, 0x1c000
	v_add_u32_e32 v166, s51, v159
	v_add_u32_e32 v182, s52, v159
	ds_read_b128 v[146:149], v166
	ds_read_b128 v[150:153], v166 offset:1024
	ds_read_b128 v[154:157], v166 offset:2048
	ds_read_b128 v[166:169], v166 offset:3072
	ds_read_b128 v[170:173], v182
	ds_read_b128 v[174:177], v182 offset:1024
	ds_read_b128 v[178:181], v182 offset:2048
	ds_read_b128 v[182:185], v182 offset:3072
	s_add_u32 s26, s34, 0x160000
	s_addc_u32 s27, s35, 0
	s_mov_b32 m0, s39
	v_lshl_add_u64 v[228:229], s[26:27], 0, v[130:131]
	ds_read_b128 v[186:189], v165 offset:32768
	ds_read_b128 v[190:193], v165 offset:33792
	ds_read_b128 v[194:197], v165 offset:34816
	ds_read_b128 v[198:201], v165 offset:35840
	ds_read_b128 v[204:207], v165 offset:36864
	ds_read_b128 v[208:211], v165 offset:37888
	ds_read_b128 v[212:215], v165 offset:38912
	ds_read_b128 v[216:219], v165 offset:39936
	global_load_lds_dwordx4 v[228:229], off
	v_lshl_add_u64 v[228:229], s[26:27], 0, v[132:133]
	s_mov_b32 m0, s40
	s_nop 0
	global_load_lds_dwordx4 v[228:229], off
	s_waitcnt vmcnt(8)
	s_waitcnt lgkmcnt(0)
	s_barrier
	s_setprio 1
	s_waitcnt lgkmcnt(0)
	v_mfma_f32_16x16x32_bf16 v[126:129], v[146:149], v[186:189], v[126:129]
	v_mfma_f32_16x16x32_bf16 v[122:125], v[154:157], v[186:189], v[122:125]
	v_mfma_f32_16x16x32_bf16 v[110:113], v[146:149], v[194:197], v[110:113]
	v_mfma_f32_16x16x32_bf16 v[106:109], v[154:157], v[194:197], v[106:109]
	v_mfma_f32_16x16x32_bf16 v[94:97], v[146:149], v[204:207], v[94:97]
	v_mfma_f32_16x16x32_bf16 v[90:93], v[154:157], v[204:207], v[90:93]
	v_mfma_f32_16x16x32_bf16 v[78:81], v[146:149], v[212:215], v[78:81]
	v_mfma_f32_16x16x32_bf16 v[74:77], v[154:157], v[212:215], v[74:77]
	v_mfma_f32_16x16x32_bf16 v[126:129], v[150:153], v[190:193], v[126:129]
	v_mfma_f32_16x16x32_bf16 v[122:125], v[166:169], v[190:193], v[122:125]
	v_mfma_f32_16x16x32_bf16 v[110:113], v[150:153], v[198:201], v[110:113]
	v_mfma_f32_16x16x32_bf16 v[106:109], v[166:169], v[198:201], v[106:109]
	v_mfma_f32_16x16x32_bf16 v[94:97], v[150:153], v[208:211], v[94:97]
	v_mfma_f32_16x16x32_bf16 v[90:93], v[166:169], v[208:211], v[90:93]
	v_mfma_f32_16x16x32_bf16 v[78:81], v[150:153], v[216:219], v[78:81]
	v_mfma_f32_16x16x32_bf16 v[74:77], v[166:169], v[216:219], v[74:77]
	s_setprio 0
	s_setprio 1
	v_mfma_f32_16x16x32_bf16 v[118:121], v[170:173], v[186:189], v[118:121]
	v_mfma_f32_16x16x32_bf16 v[114:117], v[178:181], v[186:189], v[114:117]
	v_mfma_f32_16x16x32_bf16 v[102:105], v[170:173], v[194:197], v[102:105]
	v_mfma_f32_16x16x32_bf16 v[98:101], v[178:181], v[194:197], v[98:101]
	v_mfma_f32_16x16x32_bf16 v[86:89], v[170:173], v[204:207], v[86:89]
	v_mfma_f32_16x16x32_bf16 v[82:85], v[178:181], v[204:207], v[82:85]
	v_mfma_f32_16x16x32_bf16 v[70:73], v[170:173], v[212:215], v[70:73]
	v_mfma_f32_16x16x32_bf16 v[66:69], v[178:181], v[212:215], v[66:69]
	v_mfma_f32_16x16x32_bf16 v[118:121], v[174:177], v[190:193], v[118:121]
	v_mfma_f32_16x16x32_bf16 v[114:117], v[182:185], v[190:193], v[114:117]
	v_mfma_f32_16x16x32_bf16 v[102:105], v[174:177], v[198:201], v[102:105]
	v_mfma_f32_16x16x32_bf16 v[98:101], v[182:185], v[198:201], v[98:101]
	v_mfma_f32_16x16x32_bf16 v[86:89], v[174:177], v[208:211], v[86:89]
	v_mfma_f32_16x16x32_bf16 v[82:85], v[182:185], v[208:211], v[82:85]
	v_mfma_f32_16x16x32_bf16 v[70:73], v[174:177], v[216:219], v[70:73]
	v_mfma_f32_16x16x32_bf16 v[66:69], v[182:185], v[216:219], v[66:69]
	s_setprio 2
	s_barrier
	s_add_i32 s26, s51, s19
	v_lshl_add_u64 v[220:221], v[220:221], 0, s[10:11]
	s_mov_b32 m0, s26
	ds_read_b128 v[186:189], v165 offset:49152
	ds_read_b128 v[190:193], v165 offset:50176
	ds_read_b128 v[194:197], v165 offset:51200
	ds_read_b128 v[198:201], v165 offset:52224
	ds_read_b128 v[204:207], v165 offset:53248
	ds_read_b128 v[208:211], v165 offset:54272
	ds_read_b128 v[212:215], v165 offset:55296
	ds_read_b128 v[216:219], v165 offset:56320
	global_load_lds_dwordx4 v[220:221], off
	s_add_i32 m0, s26, 0x2000
	s_add_u32 s26, s30, 0x160080
	v_lshl_add_u64 v[220:221], v[222:223], 0, s[10:11]
	s_addc_u32 s27, s31, 0
	s_add_i32 s30, s52, s19
	global_load_lds_dwordx4 v[220:221], off
	v_lshl_add_u64 v[220:221], s[26:27], 0, v[130:131]
	s_mov_b32 m0, s30
	s_nop 0
	global_load_lds_dwordx4 v[220:221], off
	v_lshl_add_u64 v[220:221], s[26:27], 0, v[132:133]
	s_add_i32 m0, s30, 0x2000
	s_nop 0
	global_load_lds_dwordx4 v[220:221], off
	v_lshl_add_u64 v[220:221], v[224:225], 0, s[10:11]
	s_mov_b32 m0, s41
	s_nop 0
	global_load_lds_dwordx4 v[220:221], off
	v_lshl_add_u64 v[220:221], v[226:227], 0, s[10:11]
	s_mov_b32 m0, s42
	s_nop 0
	global_load_lds_dwordx4 v[220:221], off
	s_waitcnt vmcnt(8)
	s_waitcnt lgkmcnt(0)
	s_barrier
	s_setprio 1
	s_waitcnt lgkmcnt(0)
	v_mfma_f32_16x16x32_bf16 v[62:65], v[146:149], v[186:189], v[62:65]
	v_mfma_f32_16x16x32_bf16 v[58:61], v[154:157], v[186:189], v[58:61]
	v_mfma_f32_16x16x32_bf16 v[46:49], v[146:149], v[194:197], v[46:49]
	v_mfma_f32_16x16x32_bf16 v[42:45], v[154:157], v[194:197], v[42:45]
	v_mfma_f32_16x16x32_bf16 v[30:33], v[146:149], v[204:207], v[30:33]
	v_mfma_f32_16x16x32_bf16 v[26:29], v[154:157], v[204:207], v[26:29]
	v_mfma_f32_16x16x32_bf16 v[14:17], v[146:149], v[212:215], v[14:17]
	v_mfma_f32_16x16x32_bf16 v[10:13], v[154:157], v[212:215], v[10:13]
	v_mfma_f32_16x16x32_bf16 v[62:65], v[150:153], v[190:193], v[62:65]
	v_mfma_f32_16x16x32_bf16 v[58:61], v[166:169], v[190:193], v[58:61]
	v_mfma_f32_16x16x32_bf16 v[46:49], v[150:153], v[198:201], v[46:49]
	v_mfma_f32_16x16x32_bf16 v[42:45], v[166:169], v[198:201], v[42:45]
	v_mfma_f32_16x16x32_bf16 v[30:33], v[150:153], v[208:211], v[30:33]
	v_mfma_f32_16x16x32_bf16 v[26:29], v[166:169], v[208:211], v[26:29]
	v_mfma_f32_16x16x32_bf16 v[14:17], v[150:153], v[216:219], v[14:17]
	v_mfma_f32_16x16x32_bf16 v[10:13], v[166:169], v[216:219], v[10:13]
	s_setprio 0
	s_setprio 1
	v_mfma_f32_16x16x32_bf16 v[54:57], v[170:173], v[186:189], v[54:57]
	v_mfma_f32_16x16x32_bf16 v[50:53], v[178:181], v[186:189], v[50:53]
	v_mfma_f32_16x16x32_bf16 v[38:41], v[170:173], v[194:197], v[38:41]
	v_mfma_f32_16x16x32_bf16 v[34:37], v[178:181], v[194:197], v[34:37]
	v_mfma_f32_16x16x32_bf16 v[22:25], v[170:173], v[204:207], v[22:25]
	v_mfma_f32_16x16x32_bf16 v[18:21], v[178:181], v[204:207], v[18:21]
	v_mfma_f32_16x16x32_bf16 v[6:9], v[170:173], v[212:215], v[6:9]
	v_mfma_f32_16x16x32_bf16 v[2:5], v[178:181], v[212:215], v[2:5]
	v_mfma_f32_16x16x32_bf16 v[54:57], v[174:177], v[190:193], v[54:57]
	v_mfma_f32_16x16x32_bf16 v[50:53], v[182:185], v[190:193], v[50:53]
	v_mfma_f32_16x16x32_bf16 v[38:41], v[174:177], v[198:201], v[38:41]
	v_mfma_f32_16x16x32_bf16 v[34:37], v[182:185], v[198:201], v[34:37]
	v_mfma_f32_16x16x32_bf16 v[22:25], v[174:177], v[208:211], v[22:25]
	v_mfma_f32_16x16x32_bf16 v[18:21], v[182:185], v[208:211], v[18:21]
	v_mfma_f32_16x16x32_bf16 v[6:9], v[174:177], v[216:219], v[6:9]
	v_mfma_f32_16x16x32_bf16 v[2:5], v[182:185], v[216:219], v[2:5]
	s_setprio 2
	s_barrier
	s_add_i32 s50, s50, 2
	s_add_u32 s23, s23, 0x100
	s_addc_u32 s25, s25, 0
	s_cmpk_gt_u32 s50, 0x55
	s_mov_b64 s[26:27], s[28:29]
	s_cbranch_scc0 .LBB0_2149
	s_and_b64 vcc, exec, s[12:13]
	s_cbranch_vccz .LBB0_2152
	s_barrier

.LBB0_2181:
	ds_read_b128 v[146:149], v211
	ds_read_b128 v[150:153], v211 offset:1024
	ds_read_b128 v[154:157], v211 offset:2048
	ds_read_b128 v[158:161], v211 offset:3072
	ds_read_b128 v[162:165], v212
	ds_read_b128 v[166:169], v212 offset:1024
	ds_read_b128 v[170:173], v212 offset:2048
	ds_read_b128 v[174:177], v212 offset:3072
	s_add_u32 s30, s28, 0x100
	s_addc_u32 s31, s29, 0
	s_cmpk_eq_i32 s53, 0x54
	s_cselect_b32 s37, s1, s31
	s_cselect_b32 s36, s0, s30
	s_cselect_b32 s35, s23, s27
	s_cselect_b32 s34, s22, s25
	v_lshl_add_u64 v[222:223], s[28:29], 0, v[138:139]
	s_add_i32 m0, s21, 0xc000
	ds_read_b128 v[178:181], v213
	ds_read_b128 v[182:185], v213 offset:1024
	ds_read_b128 v[186:189], v213 offset:2048
	ds_read_b128 v[190:193], v213 offset:3072
	ds_read_b128 v[194:197], v213 offset:4096
	ds_read_b128 v[198:201], v213 offset:5120
	ds_read_b128 v[214:217], v213 offset:6144
	ds_read_b128 v[218:221], v213 offset:7168
	global_load_lds_dwordx4 v[222:223], off
	v_lshl_add_u64 v[222:223], s[28:29], 0, v[140:141]
	s_add_i32 m0, s21, 0xe000
	s_nop 0
	global_load_lds_dwordx4 v[222:223], off
	s_waitcnt vmcnt(8)
	s_waitcnt lgkmcnt(0)
	s_barrier
	s_setprio 1
	s_waitcnt lgkmcnt(0)
	v_mfma_f32_16x16x32_bf16 v[126:129], v[146:149], v[178:181], v[126:129]
	v_mfma_f32_16x16x32_bf16 v[122:125], v[154:157], v[178:181], v[122:125]
	v_mfma_f32_16x16x32_bf16 v[110:113], v[146:149], v[186:189], v[110:113]
	v_mfma_f32_16x16x32_bf16 v[106:109], v[154:157], v[186:189], v[106:109]
	v_mfma_f32_16x16x32_bf16 v[94:97], v[146:149], v[194:197], v[94:97]
	v_mfma_f32_16x16x32_bf16 v[90:93], v[154:157], v[194:197], v[90:93]
	v_mfma_f32_16x16x32_bf16 v[78:81], v[146:149], v[214:217], v[78:81]
	v_mfma_f32_16x16x32_bf16 v[74:77], v[154:157], v[214:217], v[74:77]
	v_mfma_f32_16x16x32_bf16 v[126:129], v[150:153], v[182:185], v[126:129]
	v_mfma_f32_16x16x32_bf16 v[122:125], v[158:161], v[182:185], v[122:125]
	v_mfma_f32_16x16x32_bf16 v[110:113], v[150:153], v[190:193], v[110:113]
	v_mfma_f32_16x16x32_bf16 v[106:109], v[158:161], v[190:193], v[106:109]
	v_mfma_f32_16x16x32_bf16 v[94:97], v[150:153], v[198:201], v[94:97]
	v_mfma_f32_16x16x32_bf16 v[90:93], v[158:161], v[198:201], v[90:93]
	v_mfma_f32_16x16x32_bf16 v[78:81], v[150:153], v[218:221], v[78:81]
	v_mfma_f32_16x16x32_bf16 v[74:77], v[158:161], v[218:221], v[74:77]
	s_setprio 0
	s_setprio 1
	v_mfma_f32_16x16x32_bf16 v[118:121], v[162:165], v[178:181], v[118:121]
	v_mfma_f32_16x16x32_bf16 v[114:117], v[170:173], v[178:181], v[114:117]
	v_mfma_f32_16x16x32_bf16 v[102:105], v[162:165], v[186:189], v[102:105]
	v_mfma_f32_16x16x32_bf16 v[98:101], v[170:173], v[186:189], v[98:101]
	v_mfma_f32_16x16x32_bf16 v[86:89], v[162:165], v[194:197], v[86:89]
	v_mfma_f32_16x16x32_bf16 v[82:85], v[170:173], v[194:197], v[82:85]
	v_mfma_f32_16x16x32_bf16 v[70:73], v[162:165], v[214:217], v[70:73]
	v_mfma_f32_16x16x32_bf16 v[66:69], v[170:173], v[214:217], v[66:69]
	v_mfma_f32_16x16x32_bf16 v[118:121], v[166:169], v[182:185], v[118:121]
	v_mfma_f32_16x16x32_bf16 v[114:117], v[174:177], v[182:185], v[114:117]
	v_mfma_f32_16x16x32_bf16 v[102:105], v[166:169], v[190:193], v[102:105]
	v_mfma_f32_16x16x32_bf16 v[98:101], v[174:177], v[190:193], v[98:101]
	v_mfma_f32_16x16x32_bf16 v[86:89], v[166:169], v[198:201], v[86:89]
	v_mfma_f32_16x16x32_bf16 v[82:85], v[174:177], v[198:201], v[82:85]
	v_mfma_f32_16x16x32_bf16 v[70:73], v[166:169], v[218:221], v[70:73]
	v_mfma_f32_16x16x32_bf16 v[66:69], v[174:177], v[218:221], v[66:69]
	s_setprio 2
	s_barrier
	s_add_i32 s28, s47, s19
	v_lshl_add_u64 v[222:223], s[34:35], 0, v[130:131]
	s_mov_b32 m0, s28
	ds_read_b128 v[178:181], v213 offset:16384
	ds_read_b128 v[182:185], v213 offset:17408
	ds_read_b128 v[186:189], v213 offset:18432
	ds_read_b128 v[190:193], v213 offset:19456
	ds_read_b128 v[194:197], v213 offset:20480
	ds_read_b128 v[198:201], v213 offset:21504
	ds_read_b128 v[214:217], v213 offset:22528
	ds_read_b128 v[218:221], v213 offset:23552
	global_load_lds_dwordx4 v[222:223], off
	s_add_i32 m0, s28, 0x2000
	s_add_u32 s28, s34, 0x160000
	v_lshl_add_u64 v[224:225], s[34:35], 0, v[132:133]
	s_addc_u32 s29, s35, 0
	s_add_i32 s54, s48, s19
	global_load_lds_dwordx4 v[224:225], off
	v_lshl_add_u64 v[226:227], s[28:29], 0, v[130:131]
	s_mov_b32 m0, s54
	v_lshl_add_u64 v[228:229], s[36:37], 0, v[132:133]
	global_load_lds_dwordx4 v[226:227], off
	v_lshl_add_u64 v[226:227], s[28:29], 0, v[132:133]
	s_add_i32 m0, s54, 0x2000
	s_nop 0
	global_load_lds_dwordx4 v[226:227], off
	v_lshl_add_u64 v[226:227], s[36:37], 0, v[130:131]
	s_mov_b32 m0, s21
	s_nop 0
	global_load_lds_dwordx4 v[226:227], off
	s_mov_b32 m0, s38
	s_nop 0
	global_load_lds_dwordx4 v[228:229], off
	s_waitcnt vmcnt(8)
	s_waitcnt lgkmcnt(0)
	s_barrier
	s_setprio 1
	s_waitcnt lgkmcnt(0)
	v_mfma_f32_16x16x32_bf16 v[62:65], v[146:149], v[178:181], v[62:65]
	v_mfma_f32_16x16x32_bf16 v[58:61], v[154:157], v[178:181], v[58:61]
	v_mfma_f32_16x16x32_bf16 v[46:49], v[146:149], v[186:189], v[46:49]
	v_mfma_f32_16x16x32_bf16 v[42:45], v[154:157], v[186:189], v[42:45]
	v_mfma_f32_16x16x32_bf16 v[30:33], v[146:149], v[194:197], v[30:33]
	v_mfma_f32_16x16x32_bf16 v[26:29], v[154:157], v[194:197], v[26:29]
	v_mfma_f32_16x16x32_bf16 v[14:17], v[146:149], v[214:217], v[14:17]
	v_mfma_f32_16x16x32_bf16 v[10:13], v[154:157], v[214:217], v[10:13]
	v_mfma_f32_16x16x32_bf16 v[62:65], v[150:153], v[182:185], v[62:65]
	v_mfma_f32_16x16x32_bf16 v[58:61], v[158:161], v[182:185], v[58:61]
	v_mfma_f32_16x16x32_bf16 v[46:49], v[150:153], v[190:193], v[46:49]
	v_mfma_f32_16x16x32_bf16 v[42:45], v[158:161], v[190:193], v[42:45]
	v_mfma_f32_16x16x32_bf16 v[30:33], v[150:153], v[198:201], v[30:33]
	v_mfma_f32_16x16x32_bf16 v[26:29], v[158:161], v[198:201], v[26:29]
	v_mfma_f32_16x16x32_bf16 v[14:17], v[150:153], v[218:221], v[14:17]
	v_mfma_f32_16x16x32_bf16 v[10:13], v[158:161], v[218:221], v[10:13]
	s_setprio 0
	s_setprio 1
	v_mfma_f32_16x16x32_bf16 v[54:57], v[162:165], v[178:181], v[54:57]
	v_mfma_f32_16x16x32_bf16 v[50:53], v[170:173], v[178:181], v[50:53]
	v_mfma_f32_16x16x32_bf16 v[38:41], v[162:165], v[186:189], v[38:41]
	v_mfma_f32_16x16x32_bf16 v[34:37], v[170:173], v[186:189], v[34:37]
	v_mfma_f32_16x16x32_bf16 v[22:25], v[162:165], v[194:197], v[22:25]
	v_mfma_f32_16x16x32_bf16 v[18:21], v[170:173], v[194:197], v[18:21]
	v_mfma_f32_16x16x32_bf16 v[6:9], v[162:165], v[214:217], v[6:9]
	v_mfma_f32_16x16x32_bf16 v[2:5], v[170:173], v[214:217], v[2:5]
	v_mfma_f32_16x16x32_bf16 v[54:57], v[166:169], v[182:185], v[54:57]
	v_mfma_f32_16x16x32_bf16 v[50:53], v[174:177], v[182:185], v[50:53]
	v_mfma_f32_16x16x32_bf16 v[38:41], v[166:169], v[190:193], v[38:41]
	v_mfma_f32_16x16x32_bf16 v[34:37], v[174:177], v[190:193], v[34:37]
	v_mfma_f32_16x16x32_bf16 v[22:25], v[166:169], v[198:201], v[22:25]
	v_mfma_f32_16x16x32_bf16 v[18:21], v[174:177], v[198:201], v[18:21]
	v_mfma_f32_16x16x32_bf16 v[6:9], v[166:169], v[218:221], v[6:9]
	v_mfma_f32_16x16x32_bf16 v[2:5], v[174:177], v[218:221], v[2:5]
	s_setprio 2
	s_barrier
	s_add_i32 s54, 0, 0x18000
	s_add_i32 s55, 0, 0x1c000
	v_add_u32_e32 v158, s54, v205
	v_add_u32_e32 v174, s55, v205
	ds_read_b128 v[146:149], v158
	ds_read_b128 v[150:153], v158 offset:1024
	ds_read_b128 v[154:157], v158 offset:2048
	ds_read_b128 v[158:161], v158 offset:3072
	ds_read_b128 v[162:165], v174
	ds_read_b128 v[166:169], v174 offset:1024
	ds_read_b128 v[170:173], v174 offset:2048
	ds_read_b128 v[174:177], v174 offset:3072
	s_add_u32 s28, s36, 0x160000
	s_addc_u32 s29, s37, 0
	s_mov_b32 m0, s39
	v_lshl_add_u64 v[230:231], s[28:29], 0, v[130:131]
	ds_read_b128 v[178:181], v213 offset:32768
	ds_read_b128 v[182:185], v213 offset:33792
	ds_read_b128 v[186:189], v213 offset:34816
	ds_read_b128 v[190:193], v213 offset:35840
	ds_read_b128 v[194:197], v213 offset:36864
	ds_read_b128 v[198:201], v213 offset:37888
	ds_read_b128 v[214:217], v213 offset:38912
	ds_read_b128 v[218:221], v213 offset:39936
	global_load_lds_dwordx4 v[230:231], off
	v_lshl_add_u64 v[230:231], s[28:29], 0, v[132:133]
	s_mov_b32 m0, s40
	s_nop 0
	global_load_lds_dwordx4 v[230:231], off
	s_waitcnt vmcnt(8)
	s_waitcnt lgkmcnt(0)
	s_barrier
	s_setprio 1
	s_waitcnt lgkmcnt(0)
	v_mfma_f32_16x16x32_bf16 v[126:129], v[146:149], v[178:181], v[126:129]
	v_mfma_f32_16x16x32_bf16 v[122:125], v[154:157], v[178:181], v[122:125]
	v_mfma_f32_16x16x32_bf16 v[110:113], v[146:149], v[186:189], v[110:113]
	v_mfma_f32_16x16x32_bf16 v[106:109], v[154:157], v[186:189], v[106:109]
	v_mfma_f32_16x16x32_bf16 v[94:97], v[146:149], v[194:197], v[94:97]
	v_mfma_f32_16x16x32_bf16 v[90:93], v[154:157], v[194:197], v[90:93]
	v_mfma_f32_16x16x32_bf16 v[78:81], v[146:149], v[214:217], v[78:81]
	v_mfma_f32_16x16x32_bf16 v[74:77], v[154:157], v[214:217], v[74:77]
	v_mfma_f32_16x16x32_bf16 v[126:129], v[150:153], v[182:185], v[126:129]
	v_mfma_f32_16x16x32_bf16 v[122:125], v[158:161], v[182:185], v[122:125]
	v_mfma_f32_16x16x32_bf16 v[110:113], v[150:153], v[190:193], v[110:113]
	v_mfma_f32_16x16x32_bf16 v[106:109], v[158:161], v[190:193], v[106:109]
	v_mfma_f32_16x16x32_bf16 v[94:97], v[150:153], v[198:201], v[94:97]
	v_mfma_f32_16x16x32_bf16 v[90:93], v[158:161], v[198:201], v[90:93]
	v_mfma_f32_16x16x32_bf16 v[78:81], v[150:153], v[218:221], v[78:81]
	v_mfma_f32_16x16x32_bf16 v[74:77], v[158:161], v[218:221], v[74:77]
	s_setprio 0
	s_setprio 1
	v_mfma_f32_16x16x32_bf16 v[118:121], v[162:165], v[178:181], v[118:121]
	v_mfma_f32_16x16x32_bf16 v[114:117], v[170:173], v[178:181], v[114:117]
	v_mfma_f32_16x16x32_bf16 v[102:105], v[162:165], v[186:189], v[102:105]
	v_mfma_f32_16x16x32_bf16 v[98:101], v[170:173], v[186:189], v[98:101]
	v_mfma_f32_16x16x32_bf16 v[86:89], v[162:165], v[194:197], v[86:89]
	v_mfma_f32_16x16x32_bf16 v[82:85], v[170:173], v[194:197], v[82:85]
	v_mfma_f32_16x16x32_bf16 v[70:73], v[162:165], v[214:217], v[70:73]
	v_mfma_f32_16x16x32_bf16 v[66:69], v[170:173], v[214:217], v[66:69]
	v_mfma_f32_16x16x32_bf16 v[118:121], v[166:169], v[182:185], v[118:121]
	v_mfma_f32_16x16x32_bf16 v[114:117], v[174:177], v[182:185], v[114:117]
	v_mfma_f32_16x16x32_bf16 v[102:105], v[166:169], v[190:193], v[102:105]
	v_mfma_f32_16x16x32_bf16 v[98:101], v[174:177], v[190:193], v[98:101]
	v_mfma_f32_16x16x32_bf16 v[86:89], v[166:169], v[198:201], v[86:89]
	v_mfma_f32_16x16x32_bf16 v[82:85], v[174:177], v[198:201], v[82:85]
	v_mfma_f32_16x16x32_bf16 v[70:73], v[166:169], v[218:221], v[70:73]
	v_mfma_f32_16x16x32_bf16 v[66:69], v[174:177], v[218:221], v[66:69]
	s_setprio 2
	s_barrier
	s_add_i32 s28, s54, s19
	v_lshl_add_u64 v[222:223], v[222:223], 0, s[12:13]
	s_mov_b32 m0, s28
	ds_read_b128 v[178:181], v213 offset:49152
	ds_read_b128 v[182:185], v213 offset:50176
	ds_read_b128 v[186:189], v213 offset:51200
	ds_read_b128 v[190:193], v213 offset:52224
	ds_read_b128 v[194:197], v213 offset:53248
	ds_read_b128 v[198:201], v213 offset:54272
	ds_read_b128 v[214:217], v213 offset:55296
	ds_read_b128 v[218:221], v213 offset:56320
	global_load_lds_dwordx4 v[222:223], off
	s_add_i32 m0, s28, 0x2000
	s_add_u32 s28, s34, 0x160080
	v_lshl_add_u64 v[222:223], v[224:225], 0, s[12:13]
	s_addc_u32 s29, s35, 0
	s_add_i32 s34, s55, s19
	global_load_lds_dwordx4 v[222:223], off
	v_lshl_add_u64 v[222:223], s[28:29], 0, v[130:131]
	s_mov_b32 m0, s34
	s_nop 0
	global_load_lds_dwordx4 v[222:223], off
	v_lshl_add_u64 v[222:223], s[28:29], 0, v[132:133]
	s_add_i32 m0, s34, 0x2000
	s_nop 0
	global_load_lds_dwordx4 v[222:223], off
	v_lshl_add_u64 v[222:223], v[226:227], 0, s[12:13]
	s_mov_b32 m0, s41
	s_nop 0
	global_load_lds_dwordx4 v[222:223], off
	v_lshl_add_u64 v[222:223], v[228:229], 0, s[12:13]
	s_mov_b32 m0, s42
	s_nop 0
	global_load_lds_dwordx4 v[222:223], off
	s_waitcnt vmcnt(8)
	s_waitcnt lgkmcnt(0)
	s_barrier
	s_setprio 1
	s_waitcnt lgkmcnt(0)
	v_mfma_f32_16x16x32_bf16 v[62:65], v[146:149], v[178:181], v[62:65]
	v_mfma_f32_16x16x32_bf16 v[58:61], v[154:157], v[178:181], v[58:61]
	v_mfma_f32_16x16x32_bf16 v[46:49], v[146:149], v[186:189], v[46:49]
	v_mfma_f32_16x16x32_bf16 v[42:45], v[154:157], v[186:189], v[42:45]
	v_mfma_f32_16x16x32_bf16 v[30:33], v[146:149], v[194:197], v[30:33]
	v_mfma_f32_16x16x32_bf16 v[26:29], v[154:157], v[194:197], v[26:29]
	v_mfma_f32_16x16x32_bf16 v[14:17], v[146:149], v[214:217], v[14:17]
	v_mfma_f32_16x16x32_bf16 v[10:13], v[154:157], v[214:217], v[10:13]
	v_mfma_f32_16x16x32_bf16 v[62:65], v[150:153], v[182:185], v[62:65]
	v_mfma_f32_16x16x32_bf16 v[58:61], v[158:161], v[182:185], v[58:61]
	v_mfma_f32_16x16x32_bf16 v[46:49], v[150:153], v[190:193], v[46:49]
	v_mfma_f32_16x16x32_bf16 v[42:45], v[158:161], v[190:193], v[42:45]
	v_mfma_f32_16x16x32_bf16 v[30:33], v[150:153], v[198:201], v[30:33]
	v_mfma_f32_16x16x32_bf16 v[26:29], v[158:161], v[198:201], v[26:29]
	v_mfma_f32_16x16x32_bf16 v[14:17], v[150:153], v[218:221], v[14:17]
	v_mfma_f32_16x16x32_bf16 v[10:13], v[158:161], v[218:221], v[10:13]
	s_setprio 0
	s_setprio 1
	v_mfma_f32_16x16x32_bf16 v[54:57], v[162:165], v[178:181], v[54:57]
	v_mfma_f32_16x16x32_bf16 v[50:53], v[170:173], v[178:181], v[50:53]
	v_mfma_f32_16x16x32_bf16 v[38:41], v[162:165], v[186:189], v[38:41]
	v_mfma_f32_16x16x32_bf16 v[34:37], v[170:173], v[186:189], v[34:37]
	v_mfma_f32_16x16x32_bf16 v[22:25], v[162:165], v[194:197], v[22:25]
	v_mfma_f32_16x16x32_bf16 v[18:21], v[170:173], v[194:197], v[18:21]
	v_mfma_f32_16x16x32_bf16 v[6:9], v[162:165], v[214:217], v[6:9]
	v_mfma_f32_16x16x32_bf16 v[2:5], v[170:173], v[214:217], v[2:5]
	v_mfma_f32_16x16x32_bf16 v[54:57], v[166:169], v[182:185], v[54:57]
	v_mfma_f32_16x16x32_bf16 v[50:53], v[174:177], v[182:185], v[50:53]
	v_mfma_f32_16x16x32_bf16 v[38:41], v[166:169], v[190:193], v[38:41]
	v_mfma_f32_16x16x32_bf16 v[34:37], v[174:177], v[190:193], v[34:37]
	v_mfma_f32_16x16x32_bf16 v[22:25], v[166:169], v[198:201], v[22:25]
	v_mfma_f32_16x16x32_bf16 v[18:21], v[174:177], v[198:201], v[18:21]
	v_mfma_f32_16x16x32_bf16 v[6:9], v[166:169], v[218:221], v[6:9]
	v_mfma_f32_16x16x32_bf16 v[2:5], v[174:177], v[218:221], v[2:5]
	s_setprio 2
	s_barrier
	s_add_i32 s53, s53, 2
	s_add_u32 s25, s25, 0x100
	s_addc_u32 s27, s27, 0
	s_cmpk_gt_u32 s53, 0x55
	s_mov_b64 s[28:29], s[30:31]
	s_cbranch_scc0 .LBB0_2181
	s_and_b64 vcc, exec, s[14:15]
	s_cbranch_vccz .LBB0_2184
	s_barrier
